# EpiKV K-part: batched touch of the wave's 32 kpe/cos/sin rows ahead of the serialized per-row loads; stacked on v58
# speedup vs baseline: 1.0016x; 1.0016x over previous
; DI bf16_t to_bf16(float x) { return (bf16_t)(pack_bf16(x, 0.f) & 0xffffu); }
; DI int crow(int i, int h) { return (i & 3) + 8 * (i >> 2) + 4 * h; }
; DI float red32(float v) { v += __shfl_xor(v, 1); v += __shfl_xor(v, 2); v += __shfl_xor(v, 4); v += __shfl_xor(v, 8); v += __shfl_xor(v, 16); return v; }
;   template <int MI, int NI> DI void run(f32x16 (&acc)[MI][NI], int mb, int nb, int r, int h) const {
;     ...
;     if (nb < 1024) {
;       const int head = nb >> 7;
;       const float g0 = gk[r], g1 = gk[32 + r], g2 = gk[64 + r], g3 = gk[96 + r], g4 = gk[128 + r], g5 = gk[160 + r];
; #pragma unroll
;       for (int i = 0; i < 16; ++i) {
;         const int rw = crow(i, h), tok = mb + rw;
;         const float rkv = rsqrtf(ssq_kv[tok] * (1.f / KVL) + EPS);
;         const float v0 = acc[0][0][i] * rkv, v1 = acc[0][1][i] * rkv, v2 = acc[0][2][i] * rkv, v3 = acc[0][3][i] * rkv;
;         const float p1 = kpe[(size_t)tok * 64 + r], p2 = kpe[(size_t)tok * 64 + 32 + r];
;         float ss = v0 * v0 + v1 * v1 + v2 * v2 + v3 * v3 + p1 * p1 + p2 * p2;
;         ss = red32(ss);
;         const float rk = rsqrtf(ss * (1.f / QKH) + EPS);
;         bf16_t* kr = kout + ((size_t)(b * NH + head) * S + sb + rw) * QKH;
;         kr[r] = to_bf16(v0 * rk * g0); kr[32 + r] = to_bf16(v1 * rk * g1); kr[64 + r] = to_bf16(v2 * rk * g2); kr[96 + r] = to_bf16(v3 * rk * g3);
;         const float c = cosT[(size_t)tok * 32 + r], sn = sinT[(size_t)tok * 32 + r];
;         const float x1 = p1 * rk * g4, x2 = p2 * rk * g5;
;         kr[128 + r] = to_bf16(x1 * c - x2 * sn); kr[160 + r] = to_bf16(x2 * c + x1 * sn);
;       }
.LBB0_1266:
	s_nop 0
	v_and_b32_e32 v67, 64, v219
	v_xor_b32_e32 v66, 1, v219
	v_add_u32_e32 v67, 64, v67
	v_cmp_lt_i32_e32 vcc, v66, v67
	v_lshlrev_b32_e32 v91, 2, v96
	v_or_b32_e32 v78, v94, v91
	v_cndmask_b32_e32 v66, v219, v66, vcc
	v_lshlrev_b32_e32 v86, 2, v66
	v_xor_b32_e32 v66, 2, v219
	v_cmp_lt_i32_e32 vcc, v66, v67
	v_ashrrev_i32_e32 v79, 31, v78
	v_lshlrev_b32_e32 v0, 2, v95
	v_cndmask_b32_e32 v66, v219, v66, vcc
	v_lshlrev_b32_e32 v87, 2, v66
	v_xor_b32_e32 v66, 4, v219
	v_cmp_lt_i32_e32 vcc, v66, v67
	v_readfirstlane_b32 s31, v78
	v_lshlrev_b32_e32 v250, 7, v219
	v_and_b32_e32 v251, 31, v219
	v_lshlrev_b32_e32 v251, 7, v251
	s_lshl_b32 s32, s31, 8
	s_add_u32 s38, s48, s32
	s_addc_u32 s39, s49, 0
	s_lshl_b32 s32, s31, 7
	s_add_u32 s54, s24, s32
	s_addc_u32 s55, s25, 0
	s_add_u32 s98, s26, s32
	s_addc_u32 s99, s27, 0
	global_load_dword v252, v250, s[38:39]
	global_load_dword v252, v251, s[54:55]
	global_load_dword v252, v251, s[98:99]
	global_load_dword v85, v0, s[10:11]
	global_load_dword v84, v0, s[10:11] offset:128
	global_load_dword v83, v0, s[10:11] offset:256
	global_load_dword v82, v0, s[10:11] offset:384
	global_load_dword v81, v0, s[10:11] offset:512
	global_load_dword v80, v0, s[10:11] offset:640
	v_cndmask_b32_e32 v66, v219, v66, vcc
	v_lshlrev_b32_e32 v88, 2, v66
	v_xor_b32_e32 v66, 8, v219
	v_cmp_lt_i32_e32 vcc, v66, v67
	v_lshl_add_u64 v[72:73], s[48:49], 0, v[0:1]
	s_nop 0
	v_cndmask_b32_e32 v66, v219, v66, vcc
	v_lshlrev_b32_e32 v89, 2, v66
	v_xor_b32_e32 v66, 16, v219
	v_cmp_lt_i32_e32 vcc, v66, v67
	s_nop 1
	v_cndmask_b32_e32 v66, v219, v66, vcc
	v_lshlrev_b32_e32 v90, 2, v66
	v_add_u32_e32 v66, s13, v97
	v_lshl_add_u32 v66, v66, 3, s14
	v_ashrrev_i32_e32 v67, 31, v66
	v_lshlrev_b64 v[66:67], 14, v[66:67]
	v_lshl_add_u64 v[70:71], v[66:67], 0, v[76:77]
	v_lshl_add_u64 v[66:67], v[78:79], 2, s[84:85]
	global_load_dwordx4 v[66:69], v[66:67], off
	v_mov_b32_e32 v76, v50
	v_mov_b32_e32 v77, v2
	s_waitcnt vmcnt(0)
	v_fmamk_f32 v66, v66, 0x3b800000, v210
	v_cmp_gt_f32_e32 vcc, s29, v66
	v_mul_f32_e32 v74, 0x4b800000, v66
	s_nop 0
	v_cndmask_b32_e32 v66, v66, v74, vcc
	v_rsq_f32_e32 v66, v66
	s_nop 0
	v_mul_f32_e32 v74, 0x45800000, v66
	v_cndmask_b32_e32 v66, v66, v74, vcc
	v_lshlrev_b64 v[74:75], 8, v[78:79]
	v_lshl_add_u64 v[74:75], v[72:73], 0, v[74:75]
	global_load_dword v93, v[74:75], off
	global_load_dword v92, v[74:75], off offset:128
	v_mov_b32_e32 v74, v18
	v_mov_b32_e32 v75, v34
	v_pk_mul_f32 v[96:97], v[74:75], v[66:67] op_sel_hi:[1,0]
	v_pk_mul_f32 v[98:99], v[76:77], v[66:67] op_sel_hi:[1,0]
	v_pk_mul_f32 v[74:75], v[96:97], v[96:97]
	v_pk_mul_f32 v[76:77], v[98:99], v[98:99]
	v_add_f32_e32 v2, v74, v75
	v_add_f32_e32 v2, v77, v2
	v_add_f32_e32 v2, v76, v2
	v_mov_b64_e32 v[74:75], s[2:3]
	v_lshlrev_b32_e32 v76, 1, v95
	v_mov_b32_e32 v77, v1
	v_lshlrev_b64 v[78:79], 7, v[78:79]
	v_or_b32_e32 v78, v78, v0
	v_or_b32_e32 v95, 1, v91
	s_waitcnt vmcnt(0)
	v_pk_mul_f32 v[100:101], v[92:93], v[92:93]
	s_nop 0
	v_add_f32_e32 v2, v101, v2
	v_add_f32_e32 v2, v100, v2
	ds_bpermute_b32 v18, v86, v2
	s_waitcnt lgkmcnt(0)
	v_add_f32_e32 v2, v2, v18
	ds_bpermute_b32 v18, v87, v2
	s_waitcnt lgkmcnt(0)
	v_add_f32_e32 v2, v2, v18
	ds_bpermute_b32 v18, v88, v2
	s_waitcnt lgkmcnt(0)
	v_add_f32_e32 v2, v2, v18
	ds_bpermute_b32 v18, v89, v2
	s_waitcnt lgkmcnt(0)
	v_add_f32_e32 v2, v2, v18
	ds_bpermute_b32 v18, v90, v2
	s_waitcnt lgkmcnt(0)
	v_add_f32_e32 v2, v2, v18
	v_fmamk_f32 v2, v2, 0x3baaaaab, v210
	v_cmp_gt_f32_e32 vcc, s29, v2
	v_mul_f32_e32 v18, 0x4b800000, v2
	s_nop 0
	v_cndmask_b32_e32 v2, v2, v18, vcc
	v_rsq_f32_e32 v2, v2
	s_nop 0
	v_mul_f32_e32 v18, 0x45800000, v2
	v_cndmask_b32_e32 v2, v2, v18, vcc
	v_or_b32_e32 v18, v70, v91
	v_mad_u64_u32 v[100:101], s[0:1], v18, s65, v[74:75]
	v_mul_f32_e32 v18, v96, v2
	v_mad_i32_i24 v101, v71, s65, v101
	v_mul_f32_e32 v18, v85, v18
	v_cvt_pk_bf16_f32 v18, v18, s0
	v_lshl_add_u64 v[100:101], v[100:101], 0, v[76:77]
	global_store_short v[100:101], v18, off
	v_mul_f32_e32 v18, v97, v2
	v_mul_f32_e32 v18, v84, v18
	v_cvt_pk_bf16_f32 v18, v18, s0
	global_store_short v[100:101], v18, off offset:64
	v_mul_f32_e32 v18, v99, v2
	v_mul_f32_e32 v18, v83, v18
	v_cvt_pk_bf16_f32 v18, v18, s0
	global_store_short v[100:101], v18, off offset:128
	v_mul_f32_e32 v18, v98, v2
	v_mul_f32_e32 v18, v82, v18
	v_cvt_pk_bf16_f32 v18, v18, s0
	v_lshl_add_u64 v[96:97], s[24:25], 0, v[78:79]
	v_lshl_add_u64 v[78:79], s[26:27], 0, v[78:79]
	global_store_short v[100:101], v18, off offset:192
	global_load_dword v18, v[96:97], off
	v_mul_f32_e32 v50, v93, v2
	global_load_dword v34, v[78:79], off
	v_mul_f32_e32 v2, v92, v2
	v_mul_f32_e32 v50, v81, v50
	v_mul_f32_e32 v2, v80, v2
	v_or_b32_e32 v78, v94, v95
	v_ashrrev_i32_e32 v79, 31, v78
	s_waitcnt vmcnt(0)
	v_mul_f32_e32 v66, v34, v2
	v_mul_f32_e32 v34, v34, v50
	v_fma_f32 v66, v18, v50, -v66
	v_fmac_f32_e32 v34, v18, v2
	v_cvt_pk_bf16_f32 v66, v66, s0
	v_cvt_pk_bf16_f32 v2, v34, s0
	global_store_short v[100:101], v66, off offset:256
	global_store_short v[100:101], v2, off offset:320
	v_fmamk_f32 v2, v67, 0x3b800000, v210
	v_lshlrev_b64 v[66:67], 8, v[78:79]
	v_lshl_add_u64 v[92:93], v[72:73], 0, v[66:67]
	global_load_dword v67, v[92:93], off
	global_load_dword v66, v[92:93], off offset:128
	v_cmp_gt_f32_e32 vcc, s29, v2
	v_mul_f32_e32 v18, 0x4b800000, v2
	v_mov_b32_e32 v34, v19
	v_cndmask_b32_e32 v2, v2, v18, vcc
	v_rsq_f32_e32 v2, v2
	s_nop 0
	v_mul_f32_e32 v18, 0x45800000, v2
	v_cndmask_b32_e32 v18, v2, v18, vcc
	v_pk_mul_f32 v[34:35], v[34:35], v[18:19] op_sel_hi:[1,0]
	v_mov_b32_e32 v2, v51
	v_pk_mul_f32 v[92:93], v[34:35], v[34:35]
	v_pk_mul_f32 v[2:3], v[2:3], v[18:19] op_sel_hi:[1,0]
	v_add_f32_e32 v92, v92, v93
	v_pk_mul_f32 v[18:19], v[2:3], v[2:3]
	s_waitcnt vmcnt(0)
; DI bf16_t to_bf16(float x) { return (bf16_t)(pack_bf16(x, 0.f) & 0xffffu); }
; DI int crow(int i, int h) { return (i & 3) + 8 * (i >> 2) + 4 * h; }
; DI float red32(float v) { v += __shfl_xor(v, 1); v += __shfl_xor(v, 2); v += __shfl_xor(v, 4); v += __shfl_xor(v, 8); v += __shfl_xor(v, 16); return v; }
;   template <int MI, int NI> DI void run(f32x16 (&acc)[MI][NI], int mb, int nb, int r, int h) const {
;     ...
;       for (int i = 0; i < 16; ++i) {
;         const int rw = crow(i, h), tok = mb + rw;
;         const float rkv = rsqrtf(ssq_kv[tok] * (1.f / KVL) + EPS);
;         const float v0 = acc[0][0][i] * rkv, v1 = acc[0][1][i] * rkv, v2 = acc[0][2][i] * rkv, v3 = acc[0][3][i] * rkv;
;         const float p1 = kpe[(size_t)tok * 64 + r], p2 = kpe[(size_t)tok * 64 + 32 + r];
;         float ss = v0 * v0 + v1 * v1 + v2 * v2 + v3 * v3 + p1 * p1 + p2 * p2;
;         ss = red32(ss);
;         const float rk = rsqrtf(ss * (1.f / QKH) + EPS);
;         bf16_t* kr = kout + ((size_t)(b * NH + head) * S + sb + rw) * QKH;
;         kr[r] = to_bf16(v0 * rk * g0); kr[32 + r] = to_bf16(v1 * rk * g1); kr[64 + r] = to_bf16(v2 * rk * g2); kr[96 + r] = to_bf16(v3 * rk * g3);
;         const float c = cosT[(size_t)tok * 32 + r], sn = sinT[(size_t)tok * 32 + r];
;         const float x1 = p1 * rk * g4, x2 = p2 * rk * g5;
;         kr[128 + r] = to_bf16(x1 * c - x2 * sn); kr[160 + r] = to_bf16(x2 * c + x1 * sn);
;       }
	v_pk_mul_f32 v[50:51], v[66:67], v[66:67]
	v_add_f32_e32 v19, v19, v92
	v_add_f32_e32 v18, v18, v19
	v_add_f32_e32 v18, v51, v18
	v_add_f32_e32 v18, v50, v18
	ds_bpermute_b32 v19, v86, v18
	s_waitcnt lgkmcnt(0)
	v_add_f32_e32 v18, v18, v19
	ds_bpermute_b32 v19, v87, v18
	s_waitcnt lgkmcnt(0)
	v_add_f32_e32 v18, v18, v19
	ds_bpermute_b32 v19, v88, v18
	s_waitcnt lgkmcnt(0)
	v_add_f32_e32 v18, v18, v19
	ds_bpermute_b32 v19, v89, v18
	s_waitcnt lgkmcnt(0)
	v_add_f32_e32 v18, v18, v19
	ds_bpermute_b32 v19, v90, v18
	s_waitcnt lgkmcnt(0)
	v_add_f32_e32 v18, v18, v19
	v_fmamk_f32 v18, v18, 0x3baaaaab, v210
	v_cmp_gt_f32_e32 vcc, s29, v18
	v_mul_f32_e32 v19, 0x4b800000, v18
	s_nop 0
	v_cndmask_b32_e32 v18, v18, v19, vcc
	v_rsq_f32_e32 v18, v18
	s_nop 0
	v_mul_f32_e32 v19, 0x45800000, v18
	v_cndmask_b32_e32 v50, v18, v19, vcc
	v_or_b32_e32 v18, v70, v95
	v_mad_u64_u32 v[18:19], s[0:1], v18, s65, v[74:75]
	v_mul_f32_e32 v34, v34, v50
	v_mad_i32_i24 v19, v71, s65, v19
	v_mul_f32_e32 v34, v85, v34
	v_mul_f32_e32 v3, v3, v50
	v_mul_f32_e32 v2, v2, v50
	v_cvt_pk_bf16_f32 v34, v34, s0
	v_lshl_add_u64 v[18:19], v[18:19], 0, v[76:77]
	v_mul_f32_e32 v3, v83, v3
	v_mul_f32_e32 v2, v82, v2
	global_store_short v[18:19], v34, off
	v_mul_f32_e32 v34, v35, v50
	v_cvt_pk_bf16_f32 v3, v3, s0
	v_cvt_pk_bf16_f32 v2, v2, s0
	v_mul_f32_e32 v34, v84, v34
	global_store_short v[18:19], v3, off offset:128
	global_store_short v[18:19], v2, off offset:192
	v_lshlrev_b64 v[2:3], 7, v[78:79]
	v_cvt_pk_bf16_f32 v34, v34, s0
	v_or_b32_e32 v2, v2, v0
	global_store_short v[18:19], v34, off offset:64
	v_lshl_add_u64 v[34:35], s[24:25], 0, v[2:3]
	v_lshl_add_u64 v[2:3], s[26:27], 0, v[2:3]
	global_load_dword v34, v[34:35], off
	v_or_b32_e32 v95, 2, v91
	global_load_dword v2, v[2:3], off
	v_mul_f32_e32 v3, v67, v50
	v_mul_f32_e32 v35, v66, v50
	v_mul_f32_e32 v3, v81, v3
	v_mul_f32_e32 v35, v80, v35
	v_mov_b32_e32 v78, v52
	v_mov_b32_e32 v79, v4
	v_or_b32_e32 v52, 3, v91
	s_waitcnt vmcnt(0)
	v_mul_f32_e32 v50, v2, v35
	v_mul_f32_e32 v2, v2, v3
	v_fmac_f32_e32 v2, v34, v35
	v_cvt_pk_bf16_f32 v2, v2, s0
	global_store_short v[18:19], v2, off offset:320
	v_fmamk_f32 v2, v68, 0x3b800000, v210
	v_fma_f32 v50, v34, v3, -v50
	v_cmp_gt_f32_e32 vcc, s29, v2
	v_mul_f32_e32 v3, 0x4b800000, v2
	v_or_b32_e32 v34, v94, v95
	v_cndmask_b32_e32 v2, v2, v3, vcc
	v_rsq_f32_e32 v2, v2
	v_cvt_pk_bf16_f32 v50, v50, s0
	v_ashrrev_i32_e32 v35, 31, v34
	global_store_short v[18:19], v50, off offset:256
	v_mul_f32_e32 v3, 0x45800000, v2
	v_cndmask_b32_e32 v18, v2, v3, vcc
	v_lshlrev_b64 v[2:3], 8, v[34:35]
	v_lshl_add_u64 v[50:51], v[72:73], 0, v[2:3]
	global_load_dword v3, v[50:51], off
	global_load_dword v2, v[50:51], off offset:128
	v_mov_b32_e32 v50, v20
	v_mov_b32_e32 v51, v36
	v_pk_mul_f32 v[50:51], v[50:51], v[18:19] op_sel_hi:[1,0]
	v_pk_mul_f32 v[78:79], v[78:79], v[18:19] op_sel_hi:[1,0]
	v_pk_mul_f32 v[66:67], v[50:51], v[50:51]
	v_pk_mul_f32 v[18:19], v[78:79], v[78:79]
	v_add_f32_e32 v4, v66, v67
	v_add_f32_e32 v4, v19, v4
	v_add_f32_e32 v4, v18, v4
	v_lshlrev_b64 v[34:35], 7, v[34:35]
	v_or_b32_e32 v34, v34, v0
	v_mov_b32_e32 v36, v21
	v_or_b32_e32 v68, 8, v91
	s_waitcnt vmcnt(0)
	v_pk_mul_f32 v[92:93], v[2:3], v[2:3]
	s_nop 0
	v_add_f32_e32 v4, v93, v4
	v_add_f32_e32 v4, v92, v4
	ds_bpermute_b32 v18, v86, v4
	s_waitcnt lgkmcnt(0)
	v_add_f32_e32 v4, v4, v18
	ds_bpermute_b32 v18, v87, v4
	s_waitcnt lgkmcnt(0)
	v_add_f32_e32 v4, v4, v18
	ds_bpermute_b32 v18, v88, v4
	s_waitcnt lgkmcnt(0)
	v_add_f32_e32 v4, v4, v18
	ds_bpermute_b32 v18, v89, v4
	s_waitcnt lgkmcnt(0)
	v_add_f32_e32 v4, v4, v18
	ds_bpermute_b32 v18, v90, v4
	s_waitcnt lgkmcnt(0)
	v_add_f32_e32 v4, v4, v18
	v_fmamk_f32 v4, v4, 0x3baaaaab, v210
	v_cmp_gt_f32_e32 vcc, s29, v4
	v_mul_f32_e32 v18, 0x4b800000, v4
	s_nop 0
	v_cndmask_b32_e32 v4, v4, v18, vcc
	v_rsq_f32_e32 v4, v4
	s_nop 0
	v_mul_f32_e32 v18, 0x45800000, v4
	v_cndmask_b32_e32 v4, v4, v18, vcc
	v_or_b32_e32 v18, v70, v95
	v_mad_u64_u32 v[18:19], s[0:1], v18, s65, v[74:75]
	v_mul_f32_e32 v20, v50, v4
	v_mad_i32_i24 v19, v71, s65, v19
	v_mul_f32_e32 v20, v85, v20
	v_cvt_pk_bf16_f32 v20, v20, s0
	v_lshl_add_u64 v[18:19], v[18:19], 0, v[76:77]
	global_store_short v[18:19], v20, off
	v_mul_f32_e32 v20, v51, v4
	v_mul_f32_e32 v20, v84, v20
	v_cvt_pk_bf16_f32 v20, v20, s0
	global_store_short v[18:19], v20, off offset:64
	v_mul_f32_e32 v20, v79, v4
	v_mul_f32_e32 v20, v83, v20
	v_cvt_pk_bf16_f32 v20, v20, s0
	global_store_short v[18:19], v20, off offset:128
	v_mul_f32_e32 v20, v78, v4
	v_mul_f32_e32 v20, v82, v20
	v_cvt_pk_bf16_f32 v20, v20, s0
	v_lshl_add_u64 v[50:51], s[24:25], 0, v[34:35]
	v_lshl_add_u64 v[34:35], s[26:27], 0, v[34:35]
	global_store_short v[18:19], v20, off offset:192
	global_load_dword v20, v[50:51], off
	v_mul_f32_e32 v2, v2, v4
	global_load_dword v34, v[34:35], off
	v_mul_f32_e32 v3, v3, v4
	v_mul_f32_e32 v2, v80, v2
	v_mul_f32_e32 v3, v81, v3
	s_waitcnt vmcnt(0)
	v_mul_f32_e32 v4, v34, v2
	v_fma_f32 v4, v20, v3, -v4
	v_mul_f32_e32 v3, v34, v3
	v_fmac_f32_e32 v3, v20, v2
	v_cvt_pk_bf16_f32 v2, v3, s0
	global_store_short v[18:19], v2, off offset:320
	v_or_b32_e32 v2, v94, v52
	v_ashrrev_i32_e32 v3, 31, v2
	v_cvt_pk_bf16_f32 v4, v4, s0
	v_lshlrev_b64 v[34:35], 8, v[2:3]
	global_store_short v[18:19], v4, off offset:256
	v_lshl_add_u64 v[34:35], v[72:73], 0, v[34:35]
	global_load_dword v51, v[34:35], off
	global_load_dword v50, v[34:35], off offset:128
	v_fmamk_f32 v4, v69, 0x3b800000, v210
	v_cmp_gt_f32_e32 vcc, s29, v4
	v_mul_f32_e32 v18, 0x4b800000, v4
	v_lshlrev_b64 v[2:3], 7, v[2:3]
	v_cndmask_b32_e32 v4, v4, v18, vcc
	v_rsq_f32_e32 v4, v4
	v_or_b32_e32 v2, v2, v0
	v_mul_f32_e32 v18, 0x45800000, v4
	v_cndmask_b32_e32 v18, v4, v18, vcc
	v_pk_mul_f32 v[20:21], v[36:37], v[18:19] op_sel_hi:[1,0]
	v_mov_b32_e32 v4, v53
	v_pk_mul_f32 v[34:35], v[20:21], v[20:21]
	v_pk_mul_f32 v[4:5], v[4:5], v[18:19] op_sel_hi:[1,0]
	v_add_f32_e32 v34, v34, v35
	v_pk_mul_f32 v[18:19], v[4:5], v[4:5]
	s_waitcnt vmcnt(0)
; DI bf16_t to_bf16(float x) { return (bf16_t)(pack_bf16(x, 0.f) & 0xffffu); }
; DI int crow(int i, int h) { return (i & 3) + 8 * (i >> 2) + 4 * h; }
; DI float red32(float v) { v += __shfl_xor(v, 1); v += __shfl_xor(v, 2); v += __shfl_xor(v, 4); v += __shfl_xor(v, 8); v += __shfl_xor(v, 16); return v; }
;   template <int MI, int NI> DI void run(f32x16 (&acc)[MI][NI], int mb, int nb, int r, int h) const {
;     ...
;       for (int i = 0; i < 16; ++i) {
;         const int rw = crow(i, h), tok = mb + rw;
;         const float rkv = rsqrtf(ssq_kv[tok] * (1.f / KVL) + EPS);
;         const float v0 = acc[0][0][i] * rkv, v1 = acc[0][1][i] * rkv, v2 = acc[0][2][i] * rkv, v3 = acc[0][3][i] * rkv;
;         const float p1 = kpe[(size_t)tok * 64 + r], p2 = kpe[(size_t)tok * 64 + 32 + r];
;         float ss = v0 * v0 + v1 * v1 + v2 * v2 + v3 * v3 + p1 * p1 + p2 * p2;
;         ss = red32(ss);
;         const float rk = rsqrtf(ss * (1.f / QKH) + EPS);
;         bf16_t* kr = kout + ((size_t)(b * NH + head) * S + sb + rw) * QKH;
;         kr[r] = to_bf16(v0 * rk * g0); kr[32 + r] = to_bf16(v1 * rk * g1); kr[64 + r] = to_bf16(v2 * rk * g2); kr[96 + r] = to_bf16(v3 * rk * g3);
;         const float c = cosT[(size_t)tok * 32 + r], sn = sinT[(size_t)tok * 32 + r];
;         const float x1 = p1 * rk * g4, x2 = p2 * rk * g5;
;         kr[128 + r] = to_bf16(x1 * c - x2 * sn); kr[160 + r] = to_bf16(x2 * c + x1 * sn);
;       }
	v_pk_mul_f32 v[36:37], v[50:51], v[50:51]
	v_add_f32_e32 v19, v19, v34
	v_add_f32_e32 v18, v18, v19
	v_add_f32_e32 v18, v37, v18
	v_add_f32_e32 v18, v36, v18
	ds_bpermute_b32 v19, v86, v18
	s_waitcnt lgkmcnt(0)
	v_add_f32_e32 v18, v18, v19
	ds_bpermute_b32 v19, v87, v18
	s_waitcnt lgkmcnt(0)
	v_add_f32_e32 v18, v18, v19
	ds_bpermute_b32 v19, v88, v18
	s_waitcnt lgkmcnt(0)
	v_add_f32_e32 v18, v18, v19
	ds_bpermute_b32 v19, v89, v18
	s_waitcnt lgkmcnt(0)
	v_add_f32_e32 v18, v18, v19
	ds_bpermute_b32 v19, v90, v18
	s_waitcnt lgkmcnt(0)
	v_add_f32_e32 v18, v18, v19
	v_fmamk_f32 v18, v18, 0x3baaaaab, v210
	v_cmp_gt_f32_e32 vcc, s29, v18
	v_mul_f32_e32 v19, 0x4b800000, v18
	s_nop 0
	v_cndmask_b32_e32 v18, v18, v19, vcc
	v_rsq_f32_e32 v18, v18
	s_nop 0
	v_mul_f32_e32 v19, 0x45800000, v18
	v_cndmask_b32_e32 v34, v18, v19, vcc
	v_or_b32_e32 v18, v70, v52
	v_mad_u64_u32 v[18:19], s[0:1], v18, s65, v[74:75]
	v_mul_f32_e32 v5, v5, v34
	v_mul_f32_e32 v4, v4, v34
	v_mad_i32_i24 v19, v71, s65, v19
	v_mul_f32_e32 v5, v83, v5
	v_mul_f32_e32 v4, v82, v4
	v_lshl_add_u64 v[18:19], v[18:19], 0, v[76:77]
	v_cvt_pk_bf16_f32 v5, v5, s0
	v_cvt_pk_bf16_f32 v4, v4, s0
	global_store_short v[18:19], v5, off offset:128
	global_store_short v[18:19], v4, off offset:192
	v_lshl_add_u64 v[4:5], s[24:25], 0, v[2:3]
	v_lshl_add_u64 v[2:3], s[26:27], 0, v[2:3]
	global_load_dword v4, v[4:5], off
	v_mul_f32_e32 v20, v20, v34
	global_load_dword v2, v[2:3], off
	v_mul_f32_e32 v20, v85, v20
	v_cvt_pk_bf16_f32 v20, v20, s0
	global_store_short v[18:19], v20, off
	v_mul_f32_e32 v20, v21, v34
	v_mul_f32_e32 v20, v84, v20
	v_mul_f32_e32 v3, v51, v34
	v_mul_f32_e32 v5, v50, v34
	v_cvt_pk_bf16_f32 v20, v20, s0
	v_mul_f32_e32 v3, v81, v3
	v_mul_f32_e32 v5, v80, v5
	global_store_short v[18:19], v20, off offset:64
	v_mov_b32_e32 v50, v54
	v_mov_b32_e32 v51, v6
	s_waitcnt vmcnt(2)
	v_mul_f32_e32 v20, v2, v5
	v_mul_f32_e32 v2, v2, v3
	v_fma_f32 v20, v4, v3, -v20
	v_fmac_f32_e32 v2, v4, v5
	v_cvt_pk_bf16_f32 v20, v20, s0
	v_cvt_pk_bf16_f32 v2, v2, s0
	global_store_short v[18:19], v20, off offset:256
	global_store_short v[18:19], v2, off offset:320
	v_or_b32_e32 v18, v94, v68
	v_ashrrev_i32_e32 v19, 31, v18
	v_lshl_add_u64 v[2:3], v[18:19], 2, s[84:85]
	global_load_dwordx4 v[2:5], v[2:3], off
	s_waitcnt vmcnt(0)
	v_fmamk_f32 v2, v2, 0x3b800000, v210
	v_cmp_gt_f32_e32 vcc, s29, v2
	v_mul_f32_e32 v20, 0x4b800000, v2
	s_nop 0
	v_cndmask_b32_e32 v2, v2, v20, vcc
	v_rsq_f32_e32 v2, v2
	s_nop 0
	v_mul_f32_e32 v20, 0x45800000, v2
	v_cndmask_b32_e32 v2, v2, v20, vcc
	v_lshlrev_b64 v[20:21], 8, v[18:19]
	v_lshl_add_u64 v[34:35], v[72:73], 0, v[20:21]
	global_load_dword v21, v[34:35], off
	global_load_dword v20, v[34:35], off offset:128
	v_mov_b32_e32 v34, v22
	v_mov_b32_e32 v35, v38
	v_pk_mul_f32 v[36:37], v[34:35], v[2:3] op_sel_hi:[1,0]
	v_pk_mul_f32 v[50:51], v[50:51], v[2:3] op_sel_hi:[1,0]
	v_pk_mul_f32 v[34:35], v[36:37], v[36:37]
	v_pk_mul_f32 v[52:53], v[50:51], v[50:51]
	v_add_f32_e32 v2, v34, v35
	v_add_f32_e32 v2, v53, v2
	v_add_f32_e32 v2, v52, v2
	v_lshlrev_b64 v[18:19], 7, v[18:19]
	v_or_b32_e32 v18, v18, v0
	v_mov_b32_e32 v38, v23
	s_waitcnt vmcnt(0)
	v_pk_mul_f32 v[66:67], v[20:21], v[20:21]
	s_nop 0
	v_add_f32_e32 v2, v67, v2
	v_add_f32_e32 v2, v66, v2
	ds_bpermute_b32 v6, v86, v2
	s_waitcnt lgkmcnt(0)
	v_add_f32_e32 v2, v2, v6
	ds_bpermute_b32 v6, v87, v2
	s_waitcnt lgkmcnt(0)
	v_add_f32_e32 v2, v2, v6
	ds_bpermute_b32 v6, v88, v2
	s_waitcnt lgkmcnt(0)
	v_add_f32_e32 v2, v2, v6
	ds_bpermute_b32 v6, v89, v2
	s_waitcnt lgkmcnt(0)
	v_add_f32_e32 v2, v2, v6
	ds_bpermute_b32 v6, v90, v2
	s_waitcnt lgkmcnt(0)
	v_add_f32_e32 v2, v2, v6
	v_fmamk_f32 v2, v2, 0x3baaaaab, v210
	v_cmp_gt_f32_e32 vcc, s29, v2
	v_mul_f32_e32 v6, 0x4b800000, v2
	s_nop 0
	v_cndmask_b32_e32 v2, v2, v6, vcc
	v_rsq_f32_e32 v2, v2
	s_nop 0
	v_mul_f32_e32 v6, 0x45800000, v2
	v_cndmask_b32_e32 v2, v2, v6, vcc
	v_or_b32_e32 v6, v70, v68
	v_mad_u64_u32 v[34:35], s[0:1], v6, s65, v[74:75]
	v_mul_f32_e32 v6, v36, v2
	v_mad_i32_i24 v35, v71, s65, v35
	v_mul_f32_e32 v6, v85, v6
	v_cvt_pk_bf16_f32 v6, v6, s0
	v_lshl_add_u64 v[34:35], v[34:35], 0, v[76:77]
	global_store_short v[34:35], v6, off
	v_mul_f32_e32 v6, v37, v2
	v_mul_f32_e32 v6, v84, v6
	v_cvt_pk_bf16_f32 v6, v6, s0
	global_store_short v[34:35], v6, off offset:64
	v_mul_f32_e32 v6, v51, v2
	v_mul_f32_e32 v6, v83, v6
	v_cvt_pk_bf16_f32 v6, v6, s0
	global_store_short v[34:35], v6, off offset:128
	v_mul_f32_e32 v6, v50, v2
	v_mul_f32_e32 v6, v82, v6
	v_cvt_pk_bf16_f32 v6, v6, s0
	v_lshl_add_u64 v[36:37], s[24:25], 0, v[18:19]
	v_lshl_add_u64 v[18:19], s[26:27], 0, v[18:19]
	global_store_short v[34:35], v6, off offset:192
	global_load_dword v6, v[36:37], off
	v_or_b32_e32 v50, 9, v91
	global_load_dword v18, v[18:19], off
	v_mul_f32_e32 v19, v21, v2
	v_mul_f32_e32 v2, v20, v2
	v_mul_f32_e32 v19, v81, v19
	v_mul_f32_e32 v2, v80, v2
	s_waitcnt vmcnt(0)
	v_mul_f32_e32 v20, v18, v2
	v_mul_f32_e32 v18, v18, v19
	v_fmac_f32_e32 v18, v6, v2
	v_cvt_pk_bf16_f32 v2, v18, s0
	global_store_short v[34:35], v2, off offset:320
	v_fmamk_f32 v2, v3, 0x3b800000, v210
	v_cmp_gt_f32_e32 vcc, s29, v2
	v_mul_f32_e32 v3, 0x4b800000, v2
	v_fma_f32 v20, v6, v19, -v20
	v_cndmask_b32_e32 v2, v2, v3, vcc
	v_rsq_f32_e32 v2, v2
	v_or_b32_e32 v18, v94, v50
	v_cvt_pk_bf16_f32 v20, v20, s0
	v_ashrrev_i32_e32 v19, 31, v18
	v_mul_f32_e32 v3, 0x45800000, v2
	global_store_short v[34:35], v20, off offset:256
	v_cndmask_b32_e32 v20, v2, v3, vcc
	v_lshlrev_b64 v[2:3], 8, v[18:19]
	v_lshl_add_u64 v[34:35], v[72:73], 0, v[2:3]
	global_load_dword v3, v[34:35], off
	global_load_dword v2, v[34:35], off offset:128
	v_pk_mul_f32 v[22:23], v[38:39], v[20:21] op_sel_hi:[1,0]
	v_mov_b32_e32 v6, v55
	v_pk_mul_f32 v[34:35], v[22:23], v[22:23]
	v_pk_mul_f32 v[6:7], v[6:7], v[20:21] op_sel_hi:[1,0]
	v_add_f32_e32 v34, v34, v35
	v_pk_mul_f32 v[20:21], v[6:7], v[6:7]
	v_or_b32_e32 v38, 10, v91
	v_add_f32_e32 v21, v21, v34
	v_add_f32_e32 v20, v20, v21
	s_waitcnt vmcnt(0)
; DI bf16_t to_bf16(float x) { return (bf16_t)(pack_bf16(x, 0.f) & 0xffffu); }
; DI int crow(int i, int h) { return (i & 3) + 8 * (i >> 2) + 4 * h; }
; DI float red32(float v) { v += __shfl_xor(v, 1); v += __shfl_xor(v, 2); v += __shfl_xor(v, 4); v += __shfl_xor(v, 8); v += __shfl_xor(v, 16); return v; }
;   template <int MI, int NI> DI void run(f32x16 (&acc)[MI][NI], int mb, int nb, int r, int h) const {
;     ...
;       for (int i = 0; i < 16; ++i) {
;         const int rw = crow(i, h), tok = mb + rw;
;         const float rkv = rsqrtf(ssq_kv[tok] * (1.f / KVL) + EPS);
;         const float v0 = acc[0][0][i] * rkv, v1 = acc[0][1][i] * rkv, v2 = acc[0][2][i] * rkv, v3 = acc[0][3][i] * rkv;
;         const float p1 = kpe[(size_t)tok * 64 + r], p2 = kpe[(size_t)tok * 64 + 32 + r];
;         float ss = v0 * v0 + v1 * v1 + v2 * v2 + v3 * v3 + p1 * p1 + p2 * p2;
;         ss = red32(ss);
;         const float rk = rsqrtf(ss * (1.f / QKH) + EPS);
;         bf16_t* kr = kout + ((size_t)(b * NH + head) * S + sb + rw) * QKH;
;         kr[r] = to_bf16(v0 * rk * g0); kr[32 + r] = to_bf16(v1 * rk * g1); kr[64 + r] = to_bf16(v2 * rk * g2); kr[96 + r] = to_bf16(v3 * rk * g3);
;         const float c = cosT[(size_t)tok * 32 + r], sn = sinT[(size_t)tok * 32 + r];
;         const float x1 = p1 * rk * g4, x2 = p2 * rk * g5;
;         kr[128 + r] = to_bf16(x1 * c - x2 * sn); kr[160 + r] = to_bf16(x2 * c + x1 * sn);
;       }
	v_pk_mul_f32 v[36:37], v[2:3], v[2:3]
	s_nop 0
	v_add_f32_e32 v20, v37, v20
	v_add_f32_e32 v20, v36, v20
	ds_bpermute_b32 v21, v86, v20
	s_waitcnt lgkmcnt(0)
	v_add_f32_e32 v20, v20, v21
	ds_bpermute_b32 v21, v87, v20
	s_waitcnt lgkmcnt(0)
	v_add_f32_e32 v20, v20, v21
	ds_bpermute_b32 v21, v88, v20
	s_waitcnt lgkmcnt(0)
	v_add_f32_e32 v20, v20, v21
	ds_bpermute_b32 v21, v89, v20
	s_waitcnt lgkmcnt(0)
	v_add_f32_e32 v20, v20, v21
	ds_bpermute_b32 v21, v90, v20
	s_waitcnt lgkmcnt(0)
	v_add_f32_e32 v20, v20, v21
	v_fmamk_f32 v20, v20, 0x3baaaaab, v210
	v_cmp_gt_f32_e32 vcc, s29, v20
	v_mul_f32_e32 v21, 0x4b800000, v20
	s_nop 0
	v_cndmask_b32_e32 v20, v20, v21, vcc
	v_rsq_f32_e32 v20, v20
	s_nop 0
	v_mul_f32_e32 v21, 0x45800000, v20
	v_cndmask_b32_e32 v34, v20, v21, vcc
	v_or_b32_e32 v20, v70, v50
	v_mad_u64_u32 v[20:21], s[0:1], v20, s65, v[74:75]
	v_mul_f32_e32 v7, v7, v34
	v_mul_f32_e32 v6, v6, v34
	v_mad_i32_i24 v21, v71, s65, v21
	v_mul_f32_e32 v7, v83, v7
	v_mul_f32_e32 v6, v82, v6
	v_lshl_add_u64 v[20:21], v[20:21], 0, v[76:77]
	v_cvt_pk_bf16_f32 v7, v7, s0
	v_cvt_pk_bf16_f32 v6, v6, s0
	global_store_short v[20:21], v7, off offset:128
	global_store_short v[20:21], v6, off offset:192
	v_lshlrev_b64 v[6:7], 7, v[18:19]
	v_or_b32_e32 v6, v6, v0
	v_lshl_add_u64 v[18:19], s[24:25], 0, v[6:7]
	v_lshl_add_u64 v[6:7], s[26:27], 0, v[6:7]
	global_load_dword v18, v[18:19], off
	v_mul_f32_e32 v2, v2, v34
	global_load_dword v6, v[6:7], off
	v_mul_f32_e32 v3, v3, v34
	v_mul_f32_e32 v2, v80, v2
	v_mul_f32_e32 v3, v81, v3
	v_mul_f32_e32 v22, v22, v34
	v_mul_f32_e32 v22, v85, v22
	v_cvt_pk_bf16_f32 v22, v22, s0
	global_store_short v[20:21], v22, off
	v_mul_f32_e32 v22, v23, v34
	v_mul_f32_e32 v22, v84, v22
	v_cvt_pk_bf16_f32 v22, v22, s0
	global_store_short v[20:21], v22, off offset:64
	v_mov_b32_e32 v22, v56
	v_mov_b32_e32 v23, v8
	s_waitcnt vmcnt(2)
	v_mul_f32_e32 v7, v6, v2
	v_fma_f32 v7, v18, v3, -v7
	v_mul_f32_e32 v3, v6, v3
	v_fmac_f32_e32 v3, v18, v2
	v_cvt_pk_bf16_f32 v2, v3, s0
	global_store_short v[20:21], v2, off offset:320
	v_fmamk_f32 v2, v4, 0x3b800000, v210
	v_cmp_gt_f32_e32 vcc, s29, v2
	v_mul_f32_e32 v3, 0x4b800000, v2
	v_or_b32_e32 v18, v94, v38
	v_cndmask_b32_e32 v2, v2, v3, vcc
	v_rsq_f32_e32 v2, v2
	v_ashrrev_i32_e32 v19, 31, v18
	v_cvt_pk_bf16_f32 v7, v7, s0
	global_store_short v[20:21], v7, off offset:256
	v_mul_f32_e32 v3, 0x45800000, v2
	v_cndmask_b32_e32 v4, v2, v3, vcc
	v_lshlrev_b64 v[2:3], 8, v[18:19]
	v_lshl_add_u64 v[6:7], v[72:73], 0, v[2:3]
	global_load_dword v3, v[6:7], off
	global_load_dword v2, v[6:7], off offset:128
	v_mov_b32_e32 v6, v24
	v_mov_b32_e32 v7, v40
	v_pk_mul_f32 v[20:21], v[6:7], v[4:5] op_sel_hi:[1,0]
	v_pk_mul_f32 v[22:23], v[22:23], v[4:5] op_sel_hi:[1,0]
	v_pk_mul_f32 v[6:7], v[20:21], v[20:21]
	v_pk_mul_f32 v[34:35], v[22:23], v[22:23]
	v_add_f32_e32 v4, v6, v7
	v_add_f32_e32 v4, v35, v4
	v_add_f32_e32 v4, v34, v4
	v_lshlrev_b64 v[18:19], 7, v[18:19]
	v_or_b32_e32 v18, v18, v0
	v_or_b32_e32 v24, 11, v91
	v_mov_b32_e32 v40, v25
	s_waitcnt vmcnt(0)
	v_pk_mul_f32 v[36:37], v[2:3], v[2:3]
	s_nop 0
	v_add_f32_e32 v4, v37, v4
	v_add_f32_e32 v4, v36, v4
	ds_bpermute_b32 v6, v86, v4
	v_or_b32_e32 v36, 16, v91
	s_waitcnt lgkmcnt(0)
	v_add_f32_e32 v4, v4, v6
	ds_bpermute_b32 v6, v87, v4
	s_waitcnt lgkmcnt(0)
	v_add_f32_e32 v4, v4, v6
	ds_bpermute_b32 v6, v88, v4
	s_waitcnt lgkmcnt(0)
	v_add_f32_e32 v4, v4, v6
	ds_bpermute_b32 v6, v89, v4
	s_waitcnt lgkmcnt(0)
	v_add_f32_e32 v4, v4, v6
	ds_bpermute_b32 v6, v90, v4
	s_waitcnt lgkmcnt(0)
	v_add_f32_e32 v4, v4, v6
	v_fmamk_f32 v4, v4, 0x3baaaaab, v210
	v_cmp_gt_f32_e32 vcc, s29, v4
	v_mul_f32_e32 v6, 0x4b800000, v4
	s_nop 0
	v_cndmask_b32_e32 v4, v4, v6, vcc
	v_rsq_f32_e32 v4, v4
	s_nop 0
	v_mul_f32_e32 v6, 0x45800000, v4
	v_cndmask_b32_e32 v4, v4, v6, vcc
	v_or_b32_e32 v6, v70, v38
	v_mad_u64_u32 v[6:7], s[0:1], v6, s65, v[74:75]
	v_mul_f32_e32 v8, v20, v4
	v_mad_i32_i24 v7, v71, s65, v7
	v_mul_f32_e32 v8, v85, v8
	v_cvt_pk_bf16_f32 v8, v8, s0
	v_lshl_add_u64 v[6:7], v[6:7], 0, v[76:77]
	global_store_short v[6:7], v8, off
	v_mul_f32_e32 v8, v21, v4
	v_mul_f32_e32 v8, v84, v8
	v_cvt_pk_bf16_f32 v8, v8, s0
	global_store_short v[6:7], v8, off offset:64
	v_mul_f32_e32 v8, v23, v4
	v_mul_f32_e32 v8, v83, v8
	v_cvt_pk_bf16_f32 v8, v8, s0
	global_store_short v[6:7], v8, off offset:128
	v_mul_f32_e32 v8, v22, v4
	v_mul_f32_e32 v8, v82, v8
	v_cvt_pk_bf16_f32 v8, v8, s0
	v_lshl_add_u64 v[20:21], s[24:25], 0, v[18:19]
	v_lshl_add_u64 v[18:19], s[26:27], 0, v[18:19]
	global_store_short v[6:7], v8, off offset:192
	global_load_dword v8, v[20:21], off
	v_mul_f32_e32 v2, v2, v4
	global_load_dword v18, v[18:19], off
	v_mul_f32_e32 v3, v3, v4
	v_mul_f32_e32 v2, v80, v2
	v_mul_f32_e32 v3, v81, v3
	s_waitcnt vmcnt(0)
	v_mul_f32_e32 v4, v18, v2
	v_fma_f32 v4, v8, v3, -v4
	v_mul_f32_e32 v3, v18, v3
	v_fmac_f32_e32 v3, v8, v2
	v_cvt_pk_bf16_f32 v2, v3, s0
	global_store_short v[6:7], v2, off offset:320
	v_or_b32_e32 v2, v94, v24
	v_cvt_pk_bf16_f32 v4, v4, s0
	v_ashrrev_i32_e32 v3, 31, v2
	global_store_short v[6:7], v4, off offset:256
	v_lshlrev_b64 v[6:7], 8, v[2:3]
	v_lshl_add_u64 v[6:7], v[72:73], 0, v[6:7]
	global_load_dword v19, v[6:7], off
	global_load_dword v18, v[6:7], off offset:128
	v_fmamk_f32 v4, v5, 0x3b800000, v210
	v_cmp_gt_f32_e32 vcc, s29, v4
	v_mul_f32_e32 v5, 0x4b800000, v4
	v_mov_b32_e32 v8, v57
	v_cndmask_b32_e32 v4, v4, v5, vcc
	v_rsq_f32_e32 v4, v4
	v_lshlrev_b64 v[2:3], 7, v[2:3]
	v_or_b32_e32 v2, v2, v0
	v_mul_f32_e32 v5, 0x45800000, v4
	v_cndmask_b32_e32 v4, v4, v5, vcc
	v_pk_mul_f32 v[6:7], v[40:41], v[4:5] op_sel_hi:[1,0]
	v_pk_mul_f32 v[4:5], v[8:9], v[4:5] op_sel_hi:[1,0]
	v_pk_mul_f32 v[20:21], v[6:7], v[6:7]
	v_pk_mul_f32 v[8:9], v[4:5], v[4:5]
	v_add_f32_e32 v20, v20, v21
	v_add_f32_e32 v9, v9, v20
	v_add_f32_e32 v8, v8, v9
	s_waitcnt vmcnt(0)
; DI bf16_t to_bf16(float x) { return (bf16_t)(pack_bf16(x, 0.f) & 0xffffu); }
; DI int crow(int i, int h) { return (i & 3) + 8 * (i >> 2) + 4 * h; }
; DI float red32(float v) { v += __shfl_xor(v, 1); v += __shfl_xor(v, 2); v += __shfl_xor(v, 4); v += __shfl_xor(v, 8); v += __shfl_xor(v, 16); return v; }
;   template <int MI, int NI> DI void run(f32x16 (&acc)[MI][NI], int mb, int nb, int r, int h) const {
;     ...
;       for (int i = 0; i < 16; ++i) {
;         const int rw = crow(i, h), tok = mb + rw;
;         const float rkv = rsqrtf(ssq_kv[tok] * (1.f / KVL) + EPS);
;         const float v0 = acc[0][0][i] * rkv, v1 = acc[0][1][i] * rkv, v2 = acc[0][2][i] * rkv, v3 = acc[0][3][i] * rkv;
;         const float p1 = kpe[(size_t)tok * 64 + r], p2 = kpe[(size_t)tok * 64 + 32 + r];
;         float ss = v0 * v0 + v1 * v1 + v2 * v2 + v3 * v3 + p1 * p1 + p2 * p2;
;         ss = red32(ss);
;         const float rk = rsqrtf(ss * (1.f / QKH) + EPS);
;         bf16_t* kr = kout + ((size_t)(b * NH + head) * S + sb + rw) * QKH;
;         kr[r] = to_bf16(v0 * rk * g0); kr[32 + r] = to_bf16(v1 * rk * g1); kr[64 + r] = to_bf16(v2 * rk * g2); kr[96 + r] = to_bf16(v3 * rk * g3);
;         const float c = cosT[(size_t)tok * 32 + r], sn = sinT[(size_t)tok * 32 + r];
;         const float x1 = p1 * rk * g4, x2 = p2 * rk * g5;
;         kr[128 + r] = to_bf16(x1 * c - x2 * sn); kr[160 + r] = to_bf16(x2 * c + x1 * sn);
;       }
	v_pk_mul_f32 v[22:23], v[18:19], v[18:19]
	s_nop 0
	v_add_f32_e32 v8, v23, v8
	v_add_f32_e32 v8, v22, v8
	ds_bpermute_b32 v9, v86, v8
	v_mov_b32_e32 v22, v58
	v_mov_b32_e32 v23, v10
	s_waitcnt lgkmcnt(0)
	v_add_f32_e32 v8, v8, v9
	ds_bpermute_b32 v9, v87, v8
	s_waitcnt lgkmcnt(0)
	v_add_f32_e32 v8, v8, v9
	ds_bpermute_b32 v9, v88, v8
	s_waitcnt lgkmcnt(0)
	v_add_f32_e32 v8, v8, v9
	ds_bpermute_b32 v9, v89, v8
	s_waitcnt lgkmcnt(0)
	v_add_f32_e32 v8, v8, v9
	ds_bpermute_b32 v9, v90, v8
	s_waitcnt lgkmcnt(0)
	v_add_f32_e32 v8, v8, v9
	v_fmamk_f32 v8, v8, 0x3baaaaab, v210
	v_cmp_gt_f32_e32 vcc, s29, v8
	v_mul_f32_e32 v9, 0x4b800000, v8
	s_nop 0
	v_cndmask_b32_e32 v8, v8, v9, vcc
	v_rsq_f32_e32 v8, v8
	s_nop 0
	v_mul_f32_e32 v9, 0x45800000, v8
	v_cndmask_b32_e32 v20, v8, v9, vcc
	v_or_b32_e32 v8, v70, v24
	v_mad_u64_u32 v[8:9], s[0:1], v8, s65, v[74:75]
	v_mul_f32_e32 v5, v5, v20
	v_mul_f32_e32 v4, v4, v20
	v_mad_i32_i24 v9, v71, s65, v9
	v_mul_f32_e32 v5, v83, v5
	v_mul_f32_e32 v4, v82, v4
	v_lshl_add_u64 v[8:9], v[8:9], 0, v[76:77]
	v_cvt_pk_bf16_f32 v5, v5, s0
	v_cvt_pk_bf16_f32 v4, v4, s0
	global_store_short v[8:9], v5, off offset:128
	global_store_short v[8:9], v4, off offset:192
	v_lshl_add_u64 v[4:5], s[24:25], 0, v[2:3]
	v_lshl_add_u64 v[2:3], s[26:27], 0, v[2:3]
	global_load_dword v4, v[4:5], off
	v_mul_f32_e32 v6, v6, v20
	global_load_dword v2, v[2:3], off
	v_mul_f32_e32 v6, v85, v6
	v_cvt_pk_bf16_f32 v6, v6, s0
	global_store_short v[8:9], v6, off
	v_mul_f32_e32 v6, v7, v20
	v_mul_f32_e32 v6, v84, v6
	v_mul_f32_e32 v5, v18, v20
	v_cvt_pk_bf16_f32 v6, v6, s0
	v_mul_f32_e32 v3, v19, v20
	v_mul_f32_e32 v5, v80, v5
	global_store_short v[8:9], v6, off offset:64
	v_mul_f32_e32 v3, v81, v3
	s_waitcnt vmcnt(2)
	v_mul_f32_e32 v6, v2, v5
	v_fma_f32 v6, v4, v3, -v6
	v_cvt_pk_bf16_f32 v6, v6, s0
	v_mul_f32_e32 v2, v2, v3
	global_store_short v[8:9], v6, off offset:256
	v_fmac_f32_e32 v2, v4, v5
	v_or_b32_e32 v6, v94, v36
	v_cvt_pk_bf16_f32 v2, v2, s0
	v_ashrrev_i32_e32 v7, 31, v6
	global_store_short v[8:9], v2, off offset:320
	v_lshl_add_u64 v[2:3], v[6:7], 2, s[84:85]
	global_load_dwordx4 v[2:5], v[2:3], off
	s_waitcnt vmcnt(0)
	v_fmamk_f32 v2, v2, 0x3b800000, v210
	v_cmp_gt_f32_e32 vcc, s29, v2
	v_mul_f32_e32 v8, 0x4b800000, v2
	s_nop 0
	v_cndmask_b32_e32 v2, v2, v8, vcc
	v_rsq_f32_e32 v2, v2
	s_nop 0
	v_mul_f32_e32 v8, 0x45800000, v2
	v_cndmask_b32_e32 v2, v2, v8, vcc
	v_lshlrev_b64 v[8:9], 8, v[6:7]
	v_lshl_add_u64 v[18:19], v[72:73], 0, v[8:9]
	global_load_dword v9, v[18:19], off
	global_load_dword v8, v[18:19], off offset:128
	v_mov_b32_e32 v18, v26
	v_mov_b32_e32 v19, v42
	v_pk_mul_f32 v[20:21], v[18:19], v[2:3] op_sel_hi:[1,0]
	v_pk_mul_f32 v[22:23], v[22:23], v[2:3] op_sel_hi:[1,0]
	v_pk_mul_f32 v[18:19], v[20:21], v[20:21]
	v_pk_mul_f32 v[24:25], v[22:23], v[22:23]
	v_add_f32_e32 v2, v18, v19
	v_add_f32_e32 v2, v25, v2
	v_add_f32_e32 v2, v24, v2
	v_lshlrev_b64 v[6:7], 7, v[6:7]
	v_or_b32_e32 v6, v6, v0
	v_or_b32_e32 v24, 17, v91
	v_mov_b32_e32 v42, v27
	s_waitcnt vmcnt(0)
	v_pk_mul_f32 v[34:35], v[8:9], v[8:9]
	s_nop 0
	v_add_f32_e32 v2, v35, v2
	v_add_f32_e32 v2, v34, v2
	ds_bpermute_b32 v10, v86, v2
	s_waitcnt lgkmcnt(0)
	v_add_f32_e32 v2, v2, v10
	ds_bpermute_b32 v10, v87, v2
	s_waitcnt lgkmcnt(0)
	v_add_f32_e32 v2, v2, v10
	ds_bpermute_b32 v10, v88, v2
	s_waitcnt lgkmcnt(0)
	v_add_f32_e32 v2, v2, v10
	ds_bpermute_b32 v10, v89, v2
	s_waitcnt lgkmcnt(0)
	v_add_f32_e32 v2, v2, v10
	ds_bpermute_b32 v10, v90, v2
	s_waitcnt lgkmcnt(0)
	v_add_f32_e32 v2, v2, v10
	v_fmamk_f32 v2, v2, 0x3baaaaab, v210
	v_cmp_gt_f32_e32 vcc, s29, v2
	v_mul_f32_e32 v10, 0x4b800000, v2
	s_nop 0
	v_cndmask_b32_e32 v2, v2, v10, vcc
	v_rsq_f32_e32 v2, v2
	s_nop 0
	v_mul_f32_e32 v10, 0x45800000, v2
	v_cndmask_b32_e32 v2, v2, v10, vcc
	v_or_b32_e32 v10, v70, v36
	v_mad_u64_u32 v[18:19], s[0:1], v10, s65, v[74:75]
	v_mul_f32_e32 v10, v20, v2
	v_mad_i32_i24 v19, v71, s65, v19
	v_mul_f32_e32 v10, v85, v10
	v_cvt_pk_bf16_f32 v10, v10, s0
	v_lshl_add_u64 v[18:19], v[18:19], 0, v[76:77]
	global_store_short v[18:19], v10, off
	v_mul_f32_e32 v10, v21, v2
	v_mul_f32_e32 v10, v84, v10
	v_cvt_pk_bf16_f32 v10, v10, s0
	global_store_short v[18:19], v10, off offset:64
	v_mul_f32_e32 v10, v23, v2
	v_mul_f32_e32 v10, v83, v10
	v_cvt_pk_bf16_f32 v10, v10, s0
	global_store_short v[18:19], v10, off offset:128
	v_mul_f32_e32 v10, v22, v2
	v_mul_f32_e32 v10, v82, v10
	v_cvt_pk_bf16_f32 v10, v10, s0
	v_lshl_add_u64 v[20:21], s[24:25], 0, v[6:7]
	v_lshl_add_u64 v[6:7], s[26:27], 0, v[6:7]
	global_store_short v[18:19], v10, off offset:192
	global_load_dword v10, v[20:21], off
	s_nop 0
	global_load_dword v6, v[6:7], off
	v_mul_f32_e32 v7, v9, v2
	v_mul_f32_e32 v2, v8, v2
	v_mul_f32_e32 v7, v81, v7
	v_mul_f32_e32 v2, v80, v2
	s_waitcnt vmcnt(0)
	v_mul_f32_e32 v8, v6, v2
	v_mul_f32_e32 v6, v6, v7
	v_fmac_f32_e32 v6, v10, v2
	v_cvt_pk_bf16_f32 v2, v6, s0
	global_store_short v[18:19], v2, off offset:320
	v_fmamk_f32 v2, v3, 0x3b800000, v210
	v_cmp_gt_f32_e32 vcc, s29, v2
	v_mul_f32_e32 v3, 0x4b800000, v2
	v_fma_f32 v8, v10, v7, -v8
	v_cndmask_b32_e32 v2, v2, v3, vcc
	v_rsq_f32_e32 v2, v2
	v_or_b32_e32 v6, v94, v24
	v_cvt_pk_bf16_f32 v8, v8, s0
	v_ashrrev_i32_e32 v7, 31, v6
	v_mul_f32_e32 v3, 0x45800000, v2
	global_store_short v[18:19], v8, off offset:256
	v_cndmask_b32_e32 v8, v2, v3, vcc
	v_lshlrev_b64 v[2:3], 8, v[6:7]
	v_lshl_add_u64 v[18:19], v[72:73], 0, v[2:3]
	global_load_dword v3, v[18:19], off
	global_load_dword v2, v[18:19], off offset:128
	v_pk_mul_f32 v[18:19], v[42:43], v[8:9] op_sel_hi:[1,0]
	v_mov_b32_e32 v10, v59
	v_pk_mul_f32 v[20:21], v[18:19], v[18:19]
	v_pk_mul_f32 v[8:9], v[10:11], v[8:9] op_sel_hi:[1,0]
	v_add_f32_e32 v20, v20, v21
	v_pk_mul_f32 v[10:11], v[8:9], v[8:9]
	v_lshlrev_b64 v[6:7], 7, v[6:7]
	v_add_f32_e32 v11, v11, v20
	v_add_f32_e32 v10, v10, v11
	v_or_b32_e32 v6, v6, v0
	s_waitcnt vmcnt(0)
; DI bf16_t to_bf16(float x) { return (bf16_t)(pack_bf16(x, 0.f) & 0xffffu); }
; DI int crow(int i, int h) { return (i & 3) + 8 * (i >> 2) + 4 * h; }
; DI float red32(float v) { v += __shfl_xor(v, 1); v += __shfl_xor(v, 2); v += __shfl_xor(v, 4); v += __shfl_xor(v, 8); v += __shfl_xor(v, 16); return v; }
;   template <int MI, int NI> DI void run(f32x16 (&acc)[MI][NI], int mb, int nb, int r, int h) const {
;     ...
;       for (int i = 0; i < 16; ++i) {
;         const int rw = crow(i, h), tok = mb + rw;
;         const float rkv = rsqrtf(ssq_kv[tok] * (1.f / KVL) + EPS);
;         const float v0 = acc[0][0][i] * rkv, v1 = acc[0][1][i] * rkv, v2 = acc[0][2][i] * rkv, v3 = acc[0][3][i] * rkv;
;         const float p1 = kpe[(size_t)tok * 64 + r], p2 = kpe[(size_t)tok * 64 + 32 + r];
;         float ss = v0 * v0 + v1 * v1 + v2 * v2 + v3 * v3 + p1 * p1 + p2 * p2;
;         ss = red32(ss);
;         const float rk = rsqrtf(ss * (1.f / QKH) + EPS);
;         bf16_t* kr = kout + ((size_t)(b * NH + head) * S + sb + rw) * QKH;
;         kr[r] = to_bf16(v0 * rk * g0); kr[32 + r] = to_bf16(v1 * rk * g1); kr[64 + r] = to_bf16(v2 * rk * g2); kr[96 + r] = to_bf16(v3 * rk * g3);
;         const float c = cosT[(size_t)tok * 32 + r], sn = sinT[(size_t)tok * 32 + r];
;         const float x1 = p1 * rk * g4, x2 = p2 * rk * g5;
;         kr[128 + r] = to_bf16(x1 * c - x2 * sn); kr[160 + r] = to_bf16(x2 * c + x1 * sn);
;       }
	v_pk_mul_f32 v[22:23], v[2:3], v[2:3]
	s_nop 0
	v_add_f32_e32 v10, v23, v10
	v_add_f32_e32 v10, v22, v10
	ds_bpermute_b32 v11, v86, v10
	s_waitcnt lgkmcnt(0)
	v_add_f32_e32 v10, v10, v11
	ds_bpermute_b32 v11, v87, v10
	s_waitcnt lgkmcnt(0)
	v_add_f32_e32 v10, v10, v11
	ds_bpermute_b32 v11, v88, v10
	s_waitcnt lgkmcnt(0)
	v_add_f32_e32 v10, v10, v11
	ds_bpermute_b32 v11, v89, v10
	s_waitcnt lgkmcnt(0)
	v_add_f32_e32 v10, v10, v11
	ds_bpermute_b32 v11, v90, v10
	s_waitcnt lgkmcnt(0)
	v_add_f32_e32 v10, v10, v11
	v_fmamk_f32 v10, v10, 0x3baaaaab, v210
	v_cmp_gt_f32_e32 vcc, s29, v10
	v_mul_f32_e32 v11, 0x4b800000, v10
	s_nop 0
	v_cndmask_b32_e32 v10, v10, v11, vcc
	v_rsq_f32_e32 v10, v10
	s_nop 0
	v_mul_f32_e32 v11, 0x45800000, v10
	v_cndmask_b32_e32 v20, v10, v11, vcc
	v_or_b32_e32 v10, v70, v24
	v_mad_u64_u32 v[10:11], s[0:1], v10, s65, v[74:75]
	v_mul_f32_e32 v9, v9, v20
	v_mul_f32_e32 v8, v8, v20
	v_mad_i32_i24 v11, v71, s65, v11
	v_mul_f32_e32 v9, v83, v9
	v_mul_f32_e32 v8, v82, v8
	v_lshl_add_u64 v[10:11], v[10:11], 0, v[76:77]
	v_cvt_pk_bf16_f32 v9, v9, s0
	v_cvt_pk_bf16_f32 v8, v8, s0
	global_store_short v[10:11], v9, off offset:128
	global_store_short v[10:11], v8, off offset:192
	v_lshl_add_u64 v[8:9], s[24:25], 0, v[6:7]
	v_lshl_add_u64 v[6:7], s[26:27], 0, v[6:7]
	global_load_dword v8, v[8:9], off
	v_mul_f32_e32 v2, v2, v20
	global_load_dword v6, v[6:7], off
	v_mul_f32_e32 v3, v3, v20
	v_mul_f32_e32 v2, v80, v2
	v_mul_f32_e32 v3, v81, v3
	v_mul_f32_e32 v18, v18, v20
	v_mul_f32_e32 v18, v85, v18
	v_cvt_pk_bf16_f32 v18, v18, s0
	v_or_b32_e32 v24, 18, v91
	global_store_short v[10:11], v18, off
	v_mul_f32_e32 v18, v19, v20
	v_mul_f32_e32 v18, v84, v18
	v_cvt_pk_bf16_f32 v18, v18, s0
	global_store_short v[10:11], v18, off offset:64
	v_mov_b32_e32 v18, v60
	v_mov_b32_e32 v19, v12
	v_mov_b32_e32 v12, v61
	s_waitcnt vmcnt(2)
	v_mul_f32_e32 v7, v6, v2
	v_fma_f32 v7, v8, v3, -v7
	v_mul_f32_e32 v3, v6, v3
	v_fmac_f32_e32 v3, v8, v2
	v_cvt_pk_bf16_f32 v2, v3, s0
	global_store_short v[10:11], v2, off offset:320
	v_fmamk_f32 v2, v4, 0x3b800000, v210
	v_cmp_gt_f32_e32 vcc, s29, v2
	v_mul_f32_e32 v3, 0x4b800000, v2
	v_or_b32_e32 v8, v94, v24
	v_cndmask_b32_e32 v2, v2, v3, vcc
	v_rsq_f32_e32 v2, v2
	v_ashrrev_i32_e32 v9, 31, v8
	v_cvt_pk_bf16_f32 v7, v7, s0
	global_store_short v[10:11], v7, off offset:256
	v_mul_f32_e32 v3, 0x45800000, v2
	v_cndmask_b32_e32 v4, v2, v3, vcc
	v_lshlrev_b64 v[2:3], 8, v[8:9]
	v_lshl_add_u64 v[6:7], v[72:73], 0, v[2:3]
	global_load_dword v3, v[6:7], off
	global_load_dword v2, v[6:7], off offset:128
	v_mov_b32_e32 v6, v28
	v_mov_b32_e32 v7, v44
	v_pk_mul_f32 v[10:11], v[6:7], v[4:5] op_sel_hi:[1,0]
	v_pk_mul_f32 v[18:19], v[18:19], v[4:5] op_sel_hi:[1,0]
	v_pk_mul_f32 v[6:7], v[10:11], v[10:11]
	v_pk_mul_f32 v[20:21], v[18:19], v[18:19]
	v_add_f32_e32 v4, v6, v7
	v_add_f32_e32 v4, v21, v4
	v_add_f32_e32 v4, v20, v4
	v_lshlrev_b64 v[8:9], 7, v[8:9]
	v_or_b32_e32 v8, v8, v0
	v_or_b32_e32 v20, 19, v91
	v_mov_b32_e32 v44, v29
	s_waitcnt vmcnt(0)
	v_pk_mul_f32 v[22:23], v[2:3], v[2:3]
	s_nop 0
	v_add_f32_e32 v4, v23, v4
	v_add_f32_e32 v4, v22, v4
	ds_bpermute_b32 v6, v86, v4
	s_waitcnt lgkmcnt(0)
	v_add_f32_e32 v4, v4, v6
	ds_bpermute_b32 v6, v87, v4
	s_waitcnt lgkmcnt(0)
	v_add_f32_e32 v4, v4, v6
	ds_bpermute_b32 v6, v88, v4
	s_waitcnt lgkmcnt(0)
	v_add_f32_e32 v4, v4, v6
	ds_bpermute_b32 v6, v89, v4
	s_waitcnt lgkmcnt(0)
	v_add_f32_e32 v4, v4, v6
	ds_bpermute_b32 v6, v90, v4
	s_waitcnt lgkmcnt(0)
	v_add_f32_e32 v4, v4, v6
	v_fmamk_f32 v4, v4, 0x3baaaaab, v210
	v_cmp_gt_f32_e32 vcc, s29, v4
	v_mul_f32_e32 v6, 0x4b800000, v4
	s_nop 0
	v_cndmask_b32_e32 v4, v4, v6, vcc
	v_rsq_f32_e32 v4, v4
	s_nop 0
	v_mul_f32_e32 v6, 0x45800000, v4
	v_cndmask_b32_e32 v4, v4, v6, vcc
	v_or_b32_e32 v6, v70, v24
	v_mad_u64_u32 v[6:7], s[0:1], v6, s65, v[74:75]
	v_mul_f32_e32 v10, v10, v4
	v_mad_i32_i24 v7, v71, s65, v7
	v_mul_f32_e32 v10, v85, v10
	v_cvt_pk_bf16_f32 v10, v10, s0
	v_lshl_add_u64 v[6:7], v[6:7], 0, v[76:77]
	global_store_short v[6:7], v10, off
	v_mul_f32_e32 v10, v11, v4
	v_mul_f32_e32 v10, v84, v10
	v_cvt_pk_bf16_f32 v10, v10, s0
	global_store_short v[6:7], v10, off offset:64
	v_mul_f32_e32 v10, v19, v4
	v_mul_f32_e32 v10, v83, v10
	v_cvt_pk_bf16_f32 v10, v10, s0
	global_store_short v[6:7], v10, off offset:128
	v_mul_f32_e32 v10, v18, v4
	v_mul_f32_e32 v10, v82, v10
	v_cvt_pk_bf16_f32 v10, v10, s0
	global_store_short v[6:7], v10, off offset:192
	v_lshl_add_u64 v[10:11], s[24:25], 0, v[8:9]
	v_lshl_add_u64 v[8:9], s[26:27], 0, v[8:9]
	global_load_dword v10, v[10:11], off
	v_mul_f32_e32 v2, v2, v4
	global_load_dword v8, v[8:9], off
	v_mul_f32_e32 v3, v3, v4
	v_mul_f32_e32 v2, v80, v2
	v_mul_f32_e32 v3, v81, v3
	v_or_b32_e32 v24, 24, v91
	s_waitcnt vmcnt(0)
	v_mul_f32_e32 v4, v8, v2
	v_fma_f32 v4, v10, v3, -v4
	v_mul_f32_e32 v3, v8, v3
	v_fmac_f32_e32 v3, v10, v2
	v_cvt_pk_bf16_f32 v2, v3, s0
	global_store_short v[6:7], v2, off offset:320
	v_or_b32_e32 v2, v94, v20
	v_cvt_pk_bf16_f32 v4, v4, s0
	v_ashrrev_i32_e32 v3, 31, v2
	global_store_short v[6:7], v4, off offset:256
	v_lshlrev_b64 v[6:7], 8, v[2:3]
	v_lshl_add_u64 v[6:7], v[72:73], 0, v[6:7]
	global_load_dword v9, v[6:7], off
	global_load_dword v8, v[6:7], off offset:128
	v_fmamk_f32 v4, v5, 0x3b800000, v210
	v_cmp_gt_f32_e32 vcc, s29, v4
	v_mul_f32_e32 v5, 0x4b800000, v4
	v_lshlrev_b64 v[2:3], 7, v[2:3]
	v_cndmask_b32_e32 v4, v4, v5, vcc
	v_rsq_f32_e32 v4, v4
	v_or_b32_e32 v2, v2, v0
	v_mul_f32_e32 v5, 0x45800000, v4
	v_cndmask_b32_e32 v4, v4, v5, vcc
	v_pk_mul_f32 v[6:7], v[44:45], v[4:5] op_sel_hi:[1,0]
	v_pk_mul_f32 v[4:5], v[12:13], v[4:5] op_sel_hi:[1,0]
	v_pk_mul_f32 v[10:11], v[6:7], v[6:7]
	v_pk_mul_f32 v[12:13], v[4:5], v[4:5]
	v_add_f32_e32 v10, v10, v11
	v_add_f32_e32 v10, v13, v10
	v_add_f32_e32 v10, v12, v10
	s_waitcnt vmcnt(0)
; DI bf16_t to_bf16(float x) { return (bf16_t)(pack_bf16(x, 0.f) & 0xffffu); }
; DI int crow(int i, int h) { return (i & 3) + 8 * (i >> 2) + 4 * h; }
; DI float red32(float v) { v += __shfl_xor(v, 1); v += __shfl_xor(v, 2); v += __shfl_xor(v, 4); v += __shfl_xor(v, 8); v += __shfl_xor(v, 16); return v; }
;   template <int MI, int NI> DI void run(f32x16 (&acc)[MI][NI], int mb, int nb, int r, int h) const {
;     ...
;       for (int i = 0; i < 16; ++i) {
;         const int rw = crow(i, h), tok = mb + rw;
;         const float rkv = rsqrtf(ssq_kv[tok] * (1.f / KVL) + EPS);
;         const float v0 = acc[0][0][i] * rkv, v1 = acc[0][1][i] * rkv, v2 = acc[0][2][i] * rkv, v3 = acc[0][3][i] * rkv;
;         const float p1 = kpe[(size_t)tok * 64 + r], p2 = kpe[(size_t)tok * 64 + 32 + r];
;         float ss = v0 * v0 + v1 * v1 + v2 * v2 + v3 * v3 + p1 * p1 + p2 * p2;
;         ss = red32(ss);
;         const float rk = rsqrtf(ss * (1.f / QKH) + EPS);
;         bf16_t* kr = kout + ((size_t)(b * NH + head) * S + sb + rw) * QKH;
;         kr[r] = to_bf16(v0 * rk * g0); kr[32 + r] = to_bf16(v1 * rk * g1); kr[64 + r] = to_bf16(v2 * rk * g2); kr[96 + r] = to_bf16(v3 * rk * g3);
;         const float c = cosT[(size_t)tok * 32 + r], sn = sinT[(size_t)tok * 32 + r];
;         const float x1 = p1 * rk * g4, x2 = p2 * rk * g5;
;         kr[128 + r] = to_bf16(x1 * c - x2 * sn); kr[160 + r] = to_bf16(x2 * c + x1 * sn);
;       }
	v_pk_mul_f32 v[18:19], v[8:9], v[8:9]
	s_nop 0
	v_add_f32_e32 v10, v19, v10
	v_add_f32_e32 v10, v18, v10
	ds_bpermute_b32 v11, v86, v10
	v_mov_b32_e32 v18, v62
	v_mov_b32_e32 v19, v14
	v_mov_b32_e32 v14, v63
	s_waitcnt lgkmcnt(0)
	v_add_f32_e32 v10, v10, v11
	ds_bpermute_b32 v11, v87, v10
	s_waitcnt lgkmcnt(0)
	v_add_f32_e32 v10, v10, v11
	ds_bpermute_b32 v11, v88, v10
	s_waitcnt lgkmcnt(0)
	v_add_f32_e32 v10, v10, v11
	ds_bpermute_b32 v11, v89, v10
	s_waitcnt lgkmcnt(0)
	v_add_f32_e32 v10, v10, v11
	ds_bpermute_b32 v11, v90, v10
	s_waitcnt lgkmcnt(0)
	v_add_f32_e32 v10, v10, v11
	v_fmamk_f32 v10, v10, 0x3baaaaab, v210
	v_cmp_gt_f32_e32 vcc, s29, v10
	v_mul_f32_e32 v11, 0x4b800000, v10
	s_nop 0
	v_cndmask_b32_e32 v10, v10, v11, vcc
	v_rsq_f32_e32 v10, v10
	s_nop 0
	v_mul_f32_e32 v11, 0x45800000, v10
	v_cndmask_b32_e32 v12, v10, v11, vcc
	v_or_b32_e32 v10, v70, v20
	v_mad_u64_u32 v[10:11], s[0:1], v10, s65, v[74:75]
	v_mul_f32_e32 v5, v5, v12
	v_mul_f32_e32 v4, v4, v12
	v_mad_i32_i24 v11, v71, s65, v11
	v_mul_f32_e32 v5, v83, v5
	v_mul_f32_e32 v4, v82, v4
	v_lshl_add_u64 v[10:11], v[10:11], 0, v[76:77]
	v_cvt_pk_bf16_f32 v5, v5, s0
	v_cvt_pk_bf16_f32 v4, v4, s0
	global_store_short v[10:11], v5, off offset:128
	global_store_short v[10:11], v4, off offset:192
	v_lshl_add_u64 v[4:5], s[24:25], 0, v[2:3]
	v_lshl_add_u64 v[2:3], s[26:27], 0, v[2:3]
	global_load_dword v4, v[4:5], off
	v_mul_f32_e32 v6, v6, v12
	global_load_dword v2, v[2:3], off
	v_mul_f32_e32 v6, v85, v6
	v_cvt_pk_bf16_f32 v6, v6, s0
	global_store_short v[10:11], v6, off
	v_mul_f32_e32 v6, v7, v12
	v_mul_f32_e32 v6, v84, v6
	v_mul_f32_e32 v5, v8, v12
	v_cvt_pk_bf16_f32 v6, v6, s0
	v_mul_f32_e32 v3, v9, v12
	v_mul_f32_e32 v5, v80, v5
	global_store_short v[10:11], v6, off offset:64
	v_mul_f32_e32 v3, v81, v3
	s_waitcnt vmcnt(2)
	v_mul_f32_e32 v6, v2, v5
	v_fma_f32 v6, v4, v3, -v6
	v_cvt_pk_bf16_f32 v6, v6, s0
	v_mul_f32_e32 v2, v2, v3
	global_store_short v[10:11], v6, off offset:256
	v_fmac_f32_e32 v2, v4, v5
	v_or_b32_e32 v6, v94, v24
	v_cvt_pk_bf16_f32 v2, v2, s0
	v_ashrrev_i32_e32 v7, 31, v6
	global_store_short v[10:11], v2, off offset:320
	v_lshl_add_u64 v[2:3], v[6:7], 2, s[84:85]
	global_load_dwordx4 v[2:5], v[2:3], off
	s_waitcnt vmcnt(0)
	v_fmamk_f32 v2, v2, 0x3b800000, v210
	v_cmp_gt_f32_e32 vcc, s29, v2
	v_mul_f32_e32 v8, 0x4b800000, v2
	s_nop 0
	v_cndmask_b32_e32 v2, v2, v8, vcc
	v_rsq_f32_e32 v2, v2
	s_nop 0
	v_mul_f32_e32 v8, 0x45800000, v2
	v_cndmask_b32_e32 v2, v2, v8, vcc
	v_lshlrev_b64 v[8:9], 8, v[6:7]
	v_lshl_add_u64 v[10:11], v[72:73], 0, v[8:9]
	global_load_dword v9, v[10:11], off
	global_load_dword v8, v[10:11], off offset:128
	v_mov_b32_e32 v10, v30
	v_mov_b32_e32 v11, v46
	v_pk_mul_f32 v[12:13], v[10:11], v[2:3] op_sel_hi:[1,0]
	v_pk_mul_f32 v[18:19], v[18:19], v[2:3] op_sel_hi:[1,0]
	v_pk_mul_f32 v[10:11], v[12:13], v[12:13]
	v_pk_mul_f32 v[20:21], v[18:19], v[18:19]
	v_add_f32_e32 v2, v10, v11
	v_add_f32_e32 v2, v21, v2
	v_add_f32_e32 v2, v20, v2
	v_lshlrev_b64 v[6:7], 7, v[6:7]
	v_or_b32_e32 v6, v6, v0
	v_or_b32_e32 v20, 25, v91
	v_mov_b32_e32 v46, v31
	s_waitcnt vmcnt(0)
	v_pk_mul_f32 v[22:23], v[8:9], v[8:9]
	s_nop 0
	v_add_f32_e32 v2, v23, v2
	v_add_f32_e32 v2, v22, v2
	ds_bpermute_b32 v10, v86, v2
	s_waitcnt lgkmcnt(0)
	v_add_f32_e32 v2, v2, v10
	ds_bpermute_b32 v10, v87, v2
	s_waitcnt lgkmcnt(0)
	v_add_f32_e32 v2, v2, v10
	ds_bpermute_b32 v10, v88, v2
	s_waitcnt lgkmcnt(0)
	v_add_f32_e32 v2, v2, v10
	ds_bpermute_b32 v10, v89, v2
	s_waitcnt lgkmcnt(0)
	v_add_f32_e32 v2, v2, v10
	ds_bpermute_b32 v10, v90, v2
	s_waitcnt lgkmcnt(0)
	v_add_f32_e32 v2, v2, v10
	v_fmamk_f32 v2, v2, 0x3baaaaab, v210
	v_cmp_gt_f32_e32 vcc, s29, v2
	v_mul_f32_e32 v10, 0x4b800000, v2
	s_nop 0
	v_cndmask_b32_e32 v2, v2, v10, vcc
	v_rsq_f32_e32 v2, v2
	s_nop 0
	v_mul_f32_e32 v10, 0x45800000, v2
	v_cndmask_b32_e32 v2, v2, v10, vcc
	v_or_b32_e32 v10, v70, v24
	v_mad_u64_u32 v[10:11], s[0:1], v10, s65, v[74:75]
	v_mul_f32_e32 v12, v12, v2
	v_mad_i32_i24 v11, v71, s65, v11
	v_mul_f32_e32 v12, v85, v12
	v_cvt_pk_bf16_f32 v12, v12, s0
	v_lshl_add_u64 v[10:11], v[10:11], 0, v[76:77]
	global_store_short v[10:11], v12, off
	v_mul_f32_e32 v12, v13, v2
	v_mul_f32_e32 v12, v84, v12
	v_cvt_pk_bf16_f32 v12, v12, s0
	global_store_short v[10:11], v12, off offset:64
	v_mul_f32_e32 v12, v19, v2
	v_mul_f32_e32 v12, v83, v12
	v_cvt_pk_bf16_f32 v12, v12, s0
	global_store_short v[10:11], v12, off offset:128
	v_mul_f32_e32 v12, v18, v2
	v_mul_f32_e32 v12, v82, v12
	v_cvt_pk_bf16_f32 v12, v12, s0
	global_store_short v[10:11], v12, off offset:192
	v_lshl_add_u64 v[12:13], s[24:25], 0, v[6:7]
	v_lshl_add_u64 v[6:7], s[26:27], 0, v[6:7]
	global_load_dword v12, v[12:13], off
	s_nop 0
	global_load_dword v6, v[6:7], off
	v_mul_f32_e32 v7, v9, v2
	v_mul_f32_e32 v2, v8, v2
	v_mul_f32_e32 v7, v81, v7
	v_mul_f32_e32 v2, v80, v2
	s_waitcnt vmcnt(0)
	v_mul_f32_e32 v8, v6, v2
	v_mul_f32_e32 v6, v6, v7
	v_fmac_f32_e32 v6, v12, v2
	v_cvt_pk_bf16_f32 v2, v6, s0
	global_store_short v[10:11], v2, off offset:320
	v_fmamk_f32 v2, v3, 0x3b800000, v210
	v_cmp_gt_f32_e32 vcc, s29, v2
	v_mul_f32_e32 v3, 0x4b800000, v2
	v_fma_f32 v8, v12, v7, -v8
	v_cndmask_b32_e32 v2, v2, v3, vcc
	v_rsq_f32_e32 v2, v2
	v_or_b32_e32 v6, v94, v20
	v_cvt_pk_bf16_f32 v8, v8, s0
	v_ashrrev_i32_e32 v7, 31, v6
	v_mul_f32_e32 v3, 0x45800000, v2
	global_store_short v[10:11], v8, off offset:256
	v_cndmask_b32_e32 v8, v2, v3, vcc
	v_lshlrev_b64 v[2:3], 8, v[6:7]
	v_lshl_add_u64 v[10:11], v[72:73], 0, v[2:3]
	global_load_dword v3, v[10:11], off
	global_load_dword v2, v[10:11], off offset:128
	v_pk_mul_f32 v[10:11], v[46:47], v[8:9] op_sel_hi:[1,0]
	v_pk_mul_f32 v[8:9], v[14:15], v[8:9] op_sel_hi:[1,0]
	v_pk_mul_f32 v[12:13], v[10:11], v[10:11]
	v_pk_mul_f32 v[14:15], v[8:9], v[8:9]
	v_add_f32_e32 v12, v12, v13
	v_add_f32_e32 v12, v15, v12
	v_add_f32_e32 v12, v14, v12
	v_lshlrev_b64 v[6:7], 7, v[6:7]
	v_or_b32_e32 v6, v6, v0
	s_waitcnt vmcnt(0)
; DI bf16_t to_bf16(float x) { return (bf16_t)(pack_bf16(x, 0.f) & 0xffffu); }
; DI int crow(int i, int h) { return (i & 3) + 8 * (i >> 2) + 4 * h; }
; DI float red32(float v) { v += __shfl_xor(v, 1); v += __shfl_xor(v, 2); v += __shfl_xor(v, 4); v += __shfl_xor(v, 8); v += __shfl_xor(v, 16); return v; }
;   template <int MI, int NI> DI void run(f32x16 (&acc)[MI][NI], int mb, int nb, int r, int h) const {
;     ...
;       for (int i = 0; i < 16; ++i) {
;         const int rw = crow(i, h), tok = mb + rw;
;         const float rkv = rsqrtf(ssq_kv[tok] * (1.f / KVL) + EPS);
;         const float v0 = acc[0][0][i] * rkv, v1 = acc[0][1][i] * rkv, v2 = acc[0][2][i] * rkv, v3 = acc[0][3][i] * rkv;
;         const float p1 = kpe[(size_t)tok * 64 + r], p2 = kpe[(size_t)tok * 64 + 32 + r];
;         float ss = v0 * v0 + v1 * v1 + v2 * v2 + v3 * v3 + p1 * p1 + p2 * p2;
;         ss = red32(ss);
;         const float rk = rsqrtf(ss * (1.f / QKH) + EPS);
;         bf16_t* kr = kout + ((size_t)(b * NH + head) * S + sb + rw) * QKH;
;         kr[r] = to_bf16(v0 * rk * g0); kr[32 + r] = to_bf16(v1 * rk * g1); kr[64 + r] = to_bf16(v2 * rk * g2); kr[96 + r] = to_bf16(v3 * rk * g3);
;         const float c = cosT[(size_t)tok * 32 + r], sn = sinT[(size_t)tok * 32 + r];
;         const float x1 = p1 * rk * g4, x2 = p2 * rk * g5;
;         kr[128 + r] = to_bf16(x1 * c - x2 * sn); kr[160 + r] = to_bf16(x2 * c + x1 * sn);
;       }
	v_pk_mul_f32 v[18:19], v[2:3], v[2:3]
	s_nop 0
	v_add_f32_e32 v12, v19, v12
	v_add_f32_e32 v12, v18, v12
	ds_bpermute_b32 v13, v86, v12
	s_waitcnt lgkmcnt(0)
	v_add_f32_e32 v12, v12, v13
	ds_bpermute_b32 v13, v87, v12
	s_waitcnt lgkmcnt(0)
	v_add_f32_e32 v12, v12, v13
	ds_bpermute_b32 v13, v88, v12
	s_waitcnt lgkmcnt(0)
	v_add_f32_e32 v12, v12, v13
	ds_bpermute_b32 v13, v89, v12
	s_waitcnt lgkmcnt(0)
	v_add_f32_e32 v12, v12, v13
	ds_bpermute_b32 v13, v90, v12
	s_waitcnt lgkmcnt(0)
	v_add_f32_e32 v12, v12, v13
	v_fmamk_f32 v12, v12, 0x3baaaaab, v210
	v_cmp_gt_f32_e32 vcc, s29, v12
	v_mul_f32_e32 v13, 0x4b800000, v12
	s_nop 0
	v_cndmask_b32_e32 v12, v12, v13, vcc
	v_rsq_f32_e32 v12, v12
	s_nop 0
	v_mul_f32_e32 v13, 0x45800000, v12
	v_cndmask_b32_e32 v14, v12, v13, vcc
	v_or_b32_e32 v12, v70, v20
	v_mad_u64_u32 v[12:13], s[0:1], v12, s65, v[74:75]
	v_mul_f32_e32 v9, v9, v14
	v_mul_f32_e32 v8, v8, v14
	v_mad_i32_i24 v13, v71, s65, v13
	v_mul_f32_e32 v9, v83, v9
	v_mul_f32_e32 v8, v82, v8
	v_lshl_add_u64 v[12:13], v[12:13], 0, v[76:77]
	v_cvt_pk_bf16_f32 v9, v9, s0
	v_cvt_pk_bf16_f32 v8, v8, s0
	global_store_short v[12:13], v9, off offset:128
	global_store_short v[12:13], v8, off offset:192
	v_lshl_add_u64 v[8:9], s[24:25], 0, v[6:7]
	v_lshl_add_u64 v[6:7], s[26:27], 0, v[6:7]
	global_load_dword v8, v[8:9], off
	v_mul_f32_e32 v2, v2, v14
	global_load_dword v6, v[6:7], off
	v_mul_f32_e32 v3, v3, v14
	v_mul_f32_e32 v2, v80, v2
	v_mul_f32_e32 v3, v81, v3
	v_mul_f32_e32 v10, v10, v14
	v_mul_f32_e32 v10, v85, v10
	v_cvt_pk_bf16_f32 v10, v10, s0
	v_or_b32_e32 v20, 26, v91
	global_store_short v[12:13], v10, off
	v_mul_f32_e32 v10, v11, v14
	v_mul_f32_e32 v10, v84, v10
	v_cvt_pk_bf16_f32 v10, v10, s0
	global_store_short v[12:13], v10, off offset:64
	s_waitcnt vmcnt(2)
	v_mul_f32_e32 v7, v6, v2
	v_fma_f32 v7, v8, v3, -v7
	v_mul_f32_e32 v3, v6, v3
	v_fmac_f32_e32 v3, v8, v2
	v_cvt_pk_bf16_f32 v2, v3, s0
	global_store_short v[12:13], v2, off offset:320
	v_fmamk_f32 v2, v4, 0x3b800000, v210
	v_cmp_gt_f32_e32 vcc, s29, v2
	v_mul_f32_e32 v3, 0x4b800000, v2
	v_or_b32_e32 v8, v94, v20
	v_cndmask_b32_e32 v2, v2, v3, vcc
	v_rsq_f32_e32 v2, v2
	v_ashrrev_i32_e32 v9, 31, v8
	v_cvt_pk_bf16_f32 v7, v7, s0
	global_store_short v[12:13], v7, off offset:256
	v_mul_f32_e32 v3, 0x45800000, v2
	v_cndmask_b32_e32 v4, v2, v3, vcc
	v_lshlrev_b64 v[2:3], 8, v[8:9]
	v_lshl_add_u64 v[6:7], v[72:73], 0, v[2:3]
	global_load_dword v3, v[6:7], off
	global_load_dword v2, v[6:7], off offset:128
	v_mov_b32_e32 v6, v32
	v_mov_b32_e32 v7, v48
	v_pk_mul_f32 v[10:11], v[6:7], v[4:5] op_sel_hi:[1,0]
	v_mov_b32_e32 v12, v64
	v_mov_b32_e32 v13, v16
	v_pk_mul_f32 v[6:7], v[10:11], v[10:11]
	v_pk_mul_f32 v[12:13], v[12:13], v[4:5] op_sel_hi:[1,0]
	v_add_f32_e32 v4, v6, v7
	v_pk_mul_f32 v[14:15], v[12:13], v[12:13]
	v_lshlrev_b64 v[8:9], 7, v[8:9]
	v_add_f32_e32 v4, v15, v4
	v_add_f32_e32 v4, v14, v4
	v_or_b32_e32 v8, v8, v0
	v_mov_b32_e32 v48, v33
	v_mov_b32_e32 v16, v65
	s_waitcnt vmcnt(0)
	v_pk_mul_f32 v[18:19], v[2:3], v[2:3]
	s_nop 0
	v_add_f32_e32 v4, v19, v4
	v_add_f32_e32 v4, v18, v4
	ds_bpermute_b32 v6, v86, v4
	v_or_b32_e32 v18, 27, v91
	s_waitcnt lgkmcnt(0)
	v_add_f32_e32 v4, v4, v6
	ds_bpermute_b32 v6, v87, v4
	s_waitcnt lgkmcnt(0)
	v_add_f32_e32 v4, v4, v6
	ds_bpermute_b32 v6, v88, v4
	s_waitcnt lgkmcnt(0)
	v_add_f32_e32 v4, v4, v6
	ds_bpermute_b32 v6, v89, v4
	s_waitcnt lgkmcnt(0)
	v_add_f32_e32 v4, v4, v6
	ds_bpermute_b32 v6, v90, v4
	s_waitcnt lgkmcnt(0)
; DI bf16_t to_bf16(float x) { return (bf16_t)(pack_bf16(x, 0.f) & 0xffffu); }
; DI int crow(int i, int h) { return (i & 3) + 8 * (i >> 2) + 4 * h; }
; DI float red32(float v) { v += __shfl_xor(v, 1); v += __shfl_xor(v, 2); v += __shfl_xor(v, 4); v += __shfl_xor(v, 8); v += __shfl_xor(v, 16); return v; }
;   template <int MI, int NI> DI void run(f32x16 (&acc)[MI][NI], int mb, int nb, int r, int h) const {
;     ...
;       for (int i = 0; i < 16; ++i) {
;         const int rw = crow(i, h), tok = mb + rw;
;         const float rkv = rsqrtf(ssq_kv[tok] * (1.f / KVL) + EPS);
;         const float v0 = acc[0][0][i] * rkv, v1 = acc[0][1][i] * rkv, v2 = acc[0][2][i] * rkv, v3 = acc[0][3][i] * rkv;
;         const float p1 = kpe[(size_t)tok * 64 + r], p2 = kpe[(size_t)tok * 64 + 32 + r];
;         float ss = v0 * v0 + v1 * v1 + v2 * v2 + v3 * v3 + p1 * p1 + p2 * p2;
;         ss = red32(ss);
;         const float rk = rsqrtf(ss * (1.f / QKH) + EPS);
;         bf16_t* kr = kout + ((size_t)(b * NH + head) * S + sb + rw) * QKH;
;         kr[r] = to_bf16(v0 * rk * g0); kr[32 + r] = to_bf16(v1 * rk * g1); kr[64 + r] = to_bf16(v2 * rk * g2); kr[96 + r] = to_bf16(v3 * rk * g3);
;         const float c = cosT[(size_t)tok * 32 + r], sn = sinT[(size_t)tok * 32 + r];
;         const float x1 = p1 * rk * g4, x2 = p2 * rk * g5;
;         kr[128 + r] = to_bf16(x1 * c - x2 * sn); kr[160 + r] = to_bf16(x2 * c + x1 * sn);
;       }
	v_add_f32_e32 v4, v4, v6
	v_fmamk_f32 v4, v4, 0x3baaaaab, v210
	v_cmp_gt_f32_e32 vcc, s29, v4
	v_mul_f32_e32 v6, 0x4b800000, v4
	s_nop 0
	v_cndmask_b32_e32 v4, v4, v6, vcc
	v_rsq_f32_e32 v4, v4
	s_nop 0
	v_mul_f32_e32 v6, 0x45800000, v4
	v_cndmask_b32_e32 v4, v4, v6, vcc
	v_or_b32_e32 v6, v70, v20
	v_mad_u64_u32 v[6:7], s[0:1], v6, s65, v[74:75]
	v_mul_f32_e32 v10, v10, v4
	v_mad_i32_i24 v7, v71, s65, v7
	v_mul_f32_e32 v10, v85, v10
	v_cvt_pk_bf16_f32 v10, v10, s0
	v_lshl_add_u64 v[6:7], v[6:7], 0, v[76:77]
	global_store_short v[6:7], v10, off
	v_mul_f32_e32 v10, v11, v4
	v_mul_f32_e32 v10, v84, v10
	v_cvt_pk_bf16_f32 v10, v10, s0
	global_store_short v[6:7], v10, off offset:64
	v_mul_f32_e32 v10, v13, v4
	v_mul_f32_e32 v10, v83, v10
	v_cvt_pk_bf16_f32 v10, v10, s0
	global_store_short v[6:7], v10, off offset:128
	v_mul_f32_e32 v10, v12, v4
	v_mul_f32_e32 v10, v82, v10
	v_cvt_pk_bf16_f32 v10, v10, s0
	global_store_short v[6:7], v10, off offset:192
	v_lshl_add_u64 v[10:11], s[24:25], 0, v[8:9]
	v_lshl_add_u64 v[8:9], s[26:27], 0, v[8:9]
	global_load_dword v10, v[10:11], off
	v_mul_f32_e32 v2, v2, v4
	global_load_dword v8, v[8:9], off
	v_mul_f32_e32 v3, v3, v4
	v_mul_f32_e32 v2, v80, v2
	v_mul_f32_e32 v3, v81, v3
	s_waitcnt vmcnt(0)
	v_mul_f32_e32 v4, v8, v2
	v_fma_f32 v4, v10, v3, -v4
	v_mul_f32_e32 v3, v8, v3
	v_fmac_f32_e32 v3, v10, v2
	v_cvt_pk_bf16_f32 v2, v3, s0
	global_store_short v[6:7], v2, off offset:320
	v_fmamk_f32 v2, v5, 0x3b800000, v210
	v_cmp_gt_f32_e32 vcc, s29, v2
	v_mul_f32_e32 v3, 0x4b800000, v2
	v_cvt_pk_bf16_f32 v4, v4, s0
	v_cndmask_b32_e32 v2, v2, v3, vcc
	v_rsq_f32_e32 v2, v2
	global_store_short v[6:7], v4, off offset:256
	v_or_b32_e32 v6, v94, v18
	v_ashrrev_i32_e32 v7, 31, v6
	v_mul_f32_e32 v3, 0x45800000, v2
	v_cndmask_b32_e32 v4, v2, v3, vcc
	v_lshlrev_b64 v[2:3], 8, v[6:7]
	v_lshl_add_u64 v[8:9], v[72:73], 0, v[2:3]
	global_load_dword v3, v[8:9], off
	global_load_dword v2, v[8:9], off offset:128
	v_pk_mul_f32 v[10:11], v[48:49], v[4:5] op_sel_hi:[1,0]
	v_pk_mul_f32 v[12:13], v[16:17], v[4:5] op_sel_hi:[1,0]
	v_pk_mul_f32 v[8:9], v[10:11], v[10:11]
	v_pk_mul_f32 v[4:5], v[12:13], v[12:13]
	v_add_f32_e32 v8, v8, v9
	v_add_f32_e32 v5, v5, v8
	v_add_f32_e32 v4, v4, v5
	v_lshlrev_b64 v[6:7], 7, v[6:7]
	v_or_b32_e32 v6, v6, v0
	s_waitcnt vmcnt(0)
	v_pk_mul_f32 v[14:15], v[2:3], v[2:3]
	s_nop 0
	v_add_f32_e32 v4, v15, v4
	v_add_f32_e32 v4, v14, v4
	ds_bpermute_b32 v5, v86, v4
	s_waitcnt lgkmcnt(0)
	v_add_f32_e32 v4, v4, v5
	ds_bpermute_b32 v5, v87, v4
	s_waitcnt lgkmcnt(0)
	v_add_f32_e32 v4, v4, v5
	ds_bpermute_b32 v5, v88, v4
	s_waitcnt lgkmcnt(0)
	v_add_f32_e32 v4, v4, v5
	ds_bpermute_b32 v5, v89, v4
	s_waitcnt lgkmcnt(0)
	v_add_f32_e32 v4, v4, v5
	ds_bpermute_b32 v5, v90, v4
	s_waitcnt lgkmcnt(0)
	v_add_f32_e32 v4, v4, v5
	v_fmamk_f32 v4, v4, 0x3baaaaab, v210
	v_cmp_gt_f32_e32 vcc, s29, v4
	v_mul_f32_e32 v5, 0x4b800000, v4
	s_nop 0
	v_cndmask_b32_e32 v4, v4, v5, vcc
	v_rsq_f32_e32 v4, v4
	s_nop 0
	v_mul_f32_e32 v5, 0x45800000, v4
	v_cndmask_b32_e32 v8, v4, v5, vcc
	v_or_b32_e32 v4, v70, v18
	v_mad_u64_u32 v[4:5], s[0:1], v4, s65, v[74:75]
	v_mul_f32_e32 v9, v10, v8
	v_mad_i32_i24 v5, v71, s65, v5
	v_mul_f32_e32 v9, v85, v9
	v_cvt_pk_bf16_f32 v9, v9, s0
	v_lshl_add_u64 v[4:5], v[4:5], 0, v[76:77]
	global_store_short v[4:5], v9, off
	v_mul_f32_e32 v9, v11, v8
	v_lshl_add_u64 v[10:11], s[24:25], 0, v[6:7]
	v_lshl_add_u64 v[6:7], s[26:27], 0, v[6:7]
	global_load_dword v0, v[10:11], off
	v_mul_f32_e32 v9, v84, v9
	global_load_dword v6, v[6:7], off
	v_cvt_pk_bf16_f32 v9, v9, s0
	global_store_short v[4:5], v9, off offset:64
	v_mul_f32_e32 v9, v13, v8
	v_mul_f32_e32 v2, v2, v8
	v_mul_f32_e32 v9, v83, v9
	v_mul_f32_e32 v3, v3, v8
	v_mul_f32_e32 v2, v80, v2
	v_cvt_pk_bf16_f32 v9, v9, s0
	v_mul_f32_e32 v3, v81, v3
	global_store_short v[4:5], v9, off offset:128
	v_mul_f32_e32 v9, v12, v8
	v_mul_f32_e32 v9, v82, v9
	v_cvt_pk_bf16_f32 v9, v9, s0
	global_store_short v[4:5], v9, off offset:192
	s_waitcnt vmcnt(3)
	v_mul_f32_e32 v7, v6, v2
	v_fma_f32 v7, v0, v3, -v7
	v_mul_f32_e32 v3, v6, v3
	v_fmac_f32_e32 v3, v0, v2
	v_cvt_pk_bf16_f32 v7, v7, s0
	v_cvt_pk_bf16_f32 v0, v3, s0
	global_store_short v[4:5], v7, off offset:256
	global_store_short v[4:5], v0, off offset:320
	s_branch .LBB0_1262
